# P8b EpiPle epilogue: rstd for 8 rows first, then x2/E loads in 4 pipelined quarters
# baseline (speedup 1.0000x reference)
; __device__ __forceinline__ float row_rstd(const float* ss, int row) {
;     const f32x4* p = (const f32x4*)(ss + (size_t)row * 16); const f32x4 a = p[0], b = p[1], c = p[2], d = p[3];
;     const float s = (((a[0] + a[1]) + (a[2] + a[3])) + ((b[0] + b[1]) + (b[2] + b[3]))) + (((c[0] + c[1]) + (c[2] + c[3])) + ((d[0] + d[1]) + (d[2] + d[3])));
;     return __builtin_amdgcn_rsqf(s * (1.f / DM) + EPS);
; }
;     __device__ __forceinline__ void operator()(EPI_ARGS) const {
;         const int row0 = u.pm * 256 + wr * 64 + fr, colt = u.pn * 256 + wc * 32 + 8 * fq;
; #pragma unroll
;         for (int ai = 0; ai < 2; ++ai)
; #pragma unroll
;             for (int m = 0; m < 4; ++m) { const int row = row0 + ai * 128 + m * 16; const float rs = row_rstd(ss_in, row); const size_t ro = (size_t)row * DM + colt; float s = 0.f;
; #pragma unroll
;                 for (int bj = 0; bj < 2; ++bj) { const size_t o = ro + bj * 128;
;                     const u32x4 ev = *(const u32x4*)(E + o), xv = *(const u32x4*)(x2 + o);
.LBB0_1077:
	s_lshl_b32 s0, s37, 8
	s_or_b32 s0, s0, s45
	v_ashrrev_i32_e32 v155, 1, v148
	v_and_b32_e32 v155, -8, v155
	v_add_u32_e32 v155, s0, v155
	v_and_or_b32 v222, v148, 15, s44
	v_lshl_add_u32 v222, s22, 8, v222
	v_lshlrev_b32_e32 v223, 11, v222
	v_lshl_add_u32 v223, v155, 1, v223
	v_lshlrev_b32_e32 v155, 6, v222
	s_lshl_b32 s0, s37, 4
	s_lshl_b32 s24, s43, 2
	s_add_i32 s0, s0, s24
	v_add_u32_e32 v222, s0, v155
	v_xor_b32_e32 v224, 16, v148
	v_lshlrev_b32_e32 v224, 2, v224
	v_xor_b32_e32 v225, 32, v148
	v_lshlrev_b32_e32 v225, 2, v225
	v_cmp_gt_u32_e32 vcc, 16, v148
	s_add_u32 s98, s6, 0x0
	s_addc_u32 s99, s7, 0
	global_load_dwordx4 v[156:159], v155, s[98:99]
	global_load_dwordx4 v[160:163], v155, s[98:99] offset:16
	global_load_dwordx4 v[164:167], v155, s[98:99] offset:32
	global_load_dwordx4 v[168:171], v155, s[98:99] offset:48
	global_load_dwordx4 v[172:175], v155, s[98:99] offset:1024
	global_load_dwordx4 v[176:179], v155, s[98:99] offset:1040
	global_load_dwordx4 v[180:183], v155, s[98:99] offset:1056
	global_load_dwordx4 v[186:189], v155, s[98:99] offset:1072
	global_load_dwordx4 v[190:193], v155, s[98:99] offset:2048
	global_load_dwordx4 v[194:197], v155, s[98:99] offset:2064
	global_load_dwordx4 v[198:201], v155, s[98:99] offset:2080
	global_load_dwordx4 v[202:205], v155, s[98:99] offset:2096
	global_load_dwordx4 v[206:209], v155, s[98:99] offset:3072
	global_load_dwordx4 v[210:213], v155, s[98:99] offset:3088
	global_load_dwordx4 v[214:217], v155, s[98:99] offset:3104
	global_load_dwordx4 v[218:221], v155, s[98:99] offset:3120
	s_waitcnt vmcnt(0)
	v_add_f32_e32 v156, v156, v157
	v_add_f32_e32 v158, v158, v159
	v_add_f32_e32 v160, v160, v161
	v_add_f32_e32 v162, v162, v163
	v_add_f32_e32 v164, v164, v165
	v_add_f32_e32 v166, v166, v167
	v_add_f32_e32 v168, v168, v169
	v_add_f32_e32 v170, v170, v171
	v_add_f32_e32 v156, v156, v158
	v_add_f32_e32 v160, v160, v162
	v_add_f32_e32 v164, v164, v166
	v_add_f32_e32 v168, v168, v170
	v_add_f32_e32 v156, v156, v160
	v_add_f32_e32 v164, v164, v168
	v_add_f32_e32 v156, v156, v164
	v_fmamk_f32 v156, v156, 0x3a800000, v154
	v_rsq_f32_e32 v226, v156
	v_add_f32_e32 v172, v172, v173
	v_add_f32_e32 v174, v174, v175
	v_add_f32_e32 v176, v176, v177
	v_add_f32_e32 v178, v178, v179
	v_add_f32_e32 v180, v180, v181
	v_add_f32_e32 v182, v182, v183
	v_add_f32_e32 v186, v186, v187
	v_add_f32_e32 v188, v188, v189
	v_add_f32_e32 v172, v172, v174
	v_add_f32_e32 v176, v176, v178
	v_add_f32_e32 v180, v180, v182
	v_add_f32_e32 v186, v186, v188
	v_add_f32_e32 v172, v172, v176
	v_add_f32_e32 v180, v180, v186
	v_add_f32_e32 v172, v172, v180
	v_fmamk_f32 v172, v172, 0x3a800000, v154
	v_rsq_f32_e32 v227, v172
	v_add_f32_e32 v190, v190, v191
	v_add_f32_e32 v192, v192, v193
	v_add_f32_e32 v194, v194, v195
	v_add_f32_e32 v196, v196, v197
	v_add_f32_e32 v198, v198, v199
	v_add_f32_e32 v200, v200, v201
	v_add_f32_e32 v202, v202, v203
	v_add_f32_e32 v204, v204, v205
	v_add_f32_e32 v190, v190, v192
	v_add_f32_e32 v194, v194, v196
	v_add_f32_e32 v198, v198, v200
	v_add_f32_e32 v202, v202, v204
	v_add_f32_e32 v190, v190, v194
	v_add_f32_e32 v198, v198, v202
	v_add_f32_e32 v190, v190, v198
	v_fmamk_f32 v190, v190, 0x3a800000, v154
	v_rsq_f32_e32 v228, v190
	v_add_f32_e32 v206, v206, v207
	v_add_f32_e32 v208, v208, v209
	v_add_f32_e32 v210, v210, v211
	v_add_f32_e32 v212, v212, v213
	v_add_f32_e32 v214, v214, v215
	v_add_f32_e32 v216, v216, v217
	v_add_f32_e32 v218, v218, v219
	v_add_f32_e32 v220, v220, v221
	v_add_f32_e32 v206, v206, v208
	v_add_f32_e32 v210, v210, v212
	v_add_f32_e32 v214, v214, v216
	v_add_f32_e32 v218, v218, v220
	v_add_f32_e32 v206, v206, v210
	v_add_f32_e32 v214, v214, v218
	v_add_f32_e32 v206, v206, v214
	v_fmamk_f32 v206, v206, 0x3a800000, v154
	v_rsq_f32_e32 v229, v206
	s_add_u32 s98, s6, 0x2000
	s_addc_u32 s99, s7, 0
	global_load_dwordx4 v[156:159], v155, s[98:99]
	global_load_dwordx4 v[160:163], v155, s[98:99] offset:16
	global_load_dwordx4 v[164:167], v155, s[98:99] offset:32
	global_load_dwordx4 v[168:171], v155, s[98:99] offset:48
	global_load_dwordx4 v[172:175], v155, s[98:99] offset:1024
	global_load_dwordx4 v[176:179], v155, s[98:99] offset:1040
	global_load_dwordx4 v[180:183], v155, s[98:99] offset:1056
	global_load_dwordx4 v[186:189], v155, s[98:99] offset:1072
	global_load_dwordx4 v[190:193], v155, s[98:99] offset:2048
	global_load_dwordx4 v[194:197], v155, s[98:99] offset:2064
	global_load_dwordx4 v[198:201], v155, s[98:99] offset:2080
	global_load_dwordx4 v[202:205], v155, s[98:99] offset:2096
	global_load_dwordx4 v[206:209], v155, s[98:99] offset:3072
	global_load_dwordx4 v[210:213], v155, s[98:99] offset:3088
	global_load_dwordx4 v[214:217], v155, s[98:99] offset:3104
	global_load_dwordx4 v[218:221], v155, s[98:99] offset:3120
	s_waitcnt vmcnt(0)
; __device__ __forceinline__ float fsigmoid(float v) { return __builtin_amdgcn_rcpf(1.f + __builtin_amdgcn_exp2f(-LOG2E * v)); }
; __device__ __forceinline__ u32x4 pack8(f32x4 a, f32x4 b) { u32x4 w; w.x = cvt_pk(a[0], a[1]); w.y = cvt_pk(a[2], a[3]); w.z = cvt_pk(b[0], b[1]); w.w = cvt_pk(b[2], b[3]); return w; }
;     __device__ __forceinline__ void operator()(EPI_ARGS) const {
;     ...
;             for (int m = 0; m < 4; ++m) { const int row = row0 + ai * 128 + m * 16; const float rs = row_rstd(ss_in, row); const size_t ro = (size_t)row * DM + colt; float s = 0.f;
; #pragma unroll
;                 for (int bj = 0; bj < 2; ++bj) { const size_t o = ro + bj * 128;
;                     const u32x4 ev = *(const u32x4*)(E + o), xv = *(const u32x4*)(x2 + o);
;                     f32x4 g0 = acc[ai][bj][m][0] * rs, g1 = acc[ai][bj][m][1] * rs;
; #pragma unroll
;                     for (int e = 0; e < 4; ++e) { g0[e] = fsigmoid(g0[e]); g1[e] = fsigmoid(g1[e]); }
;                     f32x4 v0, v1;
;                     v0[0] = bflo(xv.x) + g0[0] * bflo(ev.x); v0[1] = bfhi(xv.x) + g0[1] * bfhi(ev.x); v0[2] = bflo(xv.y) + g0[2] * bflo(ev.y); v0[3] = bfhi(xv.y) + g0[3] * bfhi(ev.y);
;                     v1[0] = bflo(xv.z) + g1[0] * bflo(ev.z); v1[1] = bfhi(xv.z) + g1[1] * bfhi(ev.z); v1[2] = bflo(xv.w) + g1[2] * bflo(ev.w); v1[3] = bfhi(xv.w) + g1[3] * bfhi(ev.w);
;                     *(u32x4*)(E + o) = pack8(v0, v1);
	v_add_f32_e32 v156, v156, v157
	v_add_f32_e32 v158, v158, v159
	v_add_f32_e32 v160, v160, v161
	v_add_f32_e32 v162, v162, v163
	v_add_f32_e32 v164, v164, v165
	v_add_f32_e32 v166, v166, v167
	v_add_f32_e32 v168, v168, v169
	v_add_f32_e32 v170, v170, v171
	v_add_f32_e32 v156, v156, v158
	v_add_f32_e32 v160, v160, v162
	v_add_f32_e32 v164, v164, v166
	v_add_f32_e32 v168, v168, v170
	v_add_f32_e32 v156, v156, v160
	v_add_f32_e32 v164, v164, v168
	v_add_f32_e32 v156, v156, v164
	v_fmamk_f32 v156, v156, 0x3a800000, v154
	v_rsq_f32_e32 v230, v156
	v_add_f32_e32 v172, v172, v173
	v_add_f32_e32 v174, v174, v175
	v_add_f32_e32 v176, v176, v177
	v_add_f32_e32 v178, v178, v179
	v_add_f32_e32 v180, v180, v181
	v_add_f32_e32 v182, v182, v183
	v_add_f32_e32 v186, v186, v187
	v_add_f32_e32 v188, v188, v189
	v_add_f32_e32 v172, v172, v174
	v_add_f32_e32 v176, v176, v178
	v_add_f32_e32 v180, v180, v182
	v_add_f32_e32 v186, v186, v188
	v_add_f32_e32 v172, v172, v176
	v_add_f32_e32 v180, v180, v186
	v_add_f32_e32 v172, v172, v180
	v_fmamk_f32 v172, v172, 0x3a800000, v154
	v_rsq_f32_e32 v231, v172
	v_add_f32_e32 v190, v190, v191
	v_add_f32_e32 v192, v192, v193
	v_add_f32_e32 v194, v194, v195
	v_add_f32_e32 v196, v196, v197
	v_add_f32_e32 v198, v198, v199
	v_add_f32_e32 v200, v200, v201
	v_add_f32_e32 v202, v202, v203
	v_add_f32_e32 v204, v204, v205
	v_add_f32_e32 v190, v190, v192
	v_add_f32_e32 v194, v194, v196
	v_add_f32_e32 v198, v198, v200
	v_add_f32_e32 v202, v202, v204
	v_add_f32_e32 v190, v190, v194
	v_add_f32_e32 v198, v198, v202
	v_add_f32_e32 v190, v190, v198
	v_fmamk_f32 v190, v190, 0x3a800000, v154
	v_rsq_f32_e32 v232, v190
	v_add_f32_e32 v206, v206, v207
	v_add_f32_e32 v208, v208, v209
	v_add_f32_e32 v210, v210, v211
	v_add_f32_e32 v212, v212, v213
	v_add_f32_e32 v214, v214, v215
	v_add_f32_e32 v216, v216, v217
	v_add_f32_e32 v218, v218, v219
	v_add_f32_e32 v220, v220, v221
	v_add_f32_e32 v206, v206, v208
	v_add_f32_e32 v210, v210, v212
	v_add_f32_e32 v214, v214, v216
	v_add_f32_e32 v218, v218, v220
	v_add_f32_e32 v206, v206, v210
	v_add_f32_e32 v214, v214, v218
	v_add_f32_e32 v206, v206, v214
	v_fmamk_f32 v206, v206, 0x3a800000, v154
	v_rsq_f32_e32 v233, v206
	s_add_u32 s100, s88, 0x0
	s_addc_u32 s101, s89, 0
	s_add_u32 s98, s72, 0x0
	s_addc_u32 s99, s73, 0
	global_load_dwordx4 v[156:159], v223, s[100:101]
	global_load_dwordx4 v[172:175], v223, s[98:99]
	global_load_dwordx4 v[160:163], v223, s[100:101] offset:256
	global_load_dwordx4 v[176:179], v223, s[98:99] offset:256
	s_add_u32 s100, s88, 0x8000
	s_addc_u32 s101, s89, 0
	s_add_u32 s98, s72, 0x8000
	s_addc_u32 s99, s73, 0
	global_load_dwordx4 v[164:167], v223, s[100:101]
	global_load_dwordx4 v[180:183], v223, s[98:99]
	global_load_dwordx4 v[168:171], v223, s[100:101] offset:256
	global_load_dwordx4 v[186:189], v223, s[98:99] offset:256
	s_add_u32 s100, s88, 0x10000
	s_addc_u32 s101, s89, 0
	s_add_u32 s98, s72, 0x10000
	s_addc_u32 s99, s73, 0
	global_load_dwordx4 v[190:193], v223, s[100:101]
	global_load_dwordx4 v[206:209], v223, s[98:99]
	global_load_dwordx4 v[194:197], v223, s[100:101] offset:256
	global_load_dwordx4 v[210:213], v223, s[98:99] offset:256
	s_add_u32 s100, s88, 0x18000
	s_addc_u32 s101, s89, 0
	s_add_u32 s98, s72, 0x18000
	s_addc_u32 s99, s73, 0
	global_load_dwordx4 v[198:201], v223, s[100:101]
	global_load_dwordx4 v[214:217], v223, s[98:99]
	global_load_dwordx4 v[202:205], v223, s[100:101] offset:256
	global_load_dwordx4 v[218:221], v223, s[98:99] offset:256
	s_waitcnt vmcnt(8)
	s_add_u32 s24, s72, 0x0
	s_addc_u32 s25, s73, 0
	s_add_u32 s0, s8, 0x0
	s_addc_u32 s1, s9, 0
	v_mul_f32_e32 v124, v226, v124
	v_mul_f32_e32 v125, v226, v125
	v_mul_f32_e32 v126, v226, v126
	v_mul_f32_e32 v127, v226, v127
	v_mul_f32_e32 v120, v226, v120
	v_mul_f32_e32 v121, v226, v121
	v_mul_f32_e32 v122, v226, v122
	v_mul_f32_e32 v123, v226, v123
	v_mul_f32_e32 v124, 0xbfb8aa3b, v124
	v_mul_f32_e32 v125, 0xbfb8aa3b, v125
	v_mul_f32_e32 v126, 0xbfb8aa3b, v126
	v_mul_f32_e32 v127, 0xbfb8aa3b, v127
	v_mul_f32_e32 v120, 0xbfb8aa3b, v120
	v_mul_f32_e32 v121, 0xbfb8aa3b, v121
	v_mul_f32_e32 v122, 0xbfb8aa3b, v122
	v_mul_f32_e32 v123, 0xbfb8aa3b, v123
	v_exp_f32_e32 v124, v124
	v_exp_f32_e32 v125, v125
	v_exp_f32_e32 v126, v126
	v_exp_f32_e32 v127, v127
	v_exp_f32_e32 v120, v120
	v_exp_f32_e32 v121, v121
	v_exp_f32_e32 v122, v122
	v_exp_f32_e32 v123, v123
	v_add_f32_e32 v124, 1.0, v124
	v_add_f32_e32 v125, 1.0, v125
	v_add_f32_e32 v126, 1.0, v126
	v_add_f32_e32 v127, 1.0, v127
	v_add_f32_e32 v120, 1.0, v120
	v_add_f32_e32 v121, 1.0, v121
	v_add_f32_e32 v122, 1.0, v122
	v_add_f32_e32 v123, 1.0, v123
	v_rcp_f32_e32 v124, v124
	v_rcp_f32_e32 v125, v125
	v_rcp_f32_e32 v126, v126
	v_rcp_f32_e32 v127, v127
	v_rcp_f32_e32 v120, v120
	v_rcp_f32_e32 v121, v121
	v_rcp_f32_e32 v122, v122
	v_rcp_f32_e32 v123, v123
	v_lshlrev_b32_e32 v234, 16, v172
	v_and_b32_e32 v235, 0xffff0000, v172
	v_lshlrev_b32_e32 v236, 16, v156
	v_and_b32_e32 v237, 0xffff0000, v156
	v_pk_fma_f32 v[124:125], v[124:125], v[234:235], v[236:237]
	v_lshlrev_b32_e32 v234, 16, v173
	v_and_b32_e32 v235, 0xffff0000, v173
	v_lshlrev_b32_e32 v236, 16, v157
	v_and_b32_e32 v237, 0xffff0000, v157
	v_pk_fma_f32 v[126:127], v[126:127], v[234:235], v[236:237]
	v_lshlrev_b32_e32 v234, 16, v174
	v_and_b32_e32 v235, 0xffff0000, v174
	v_lshlrev_b32_e32 v236, 16, v158
	v_and_b32_e32 v237, 0xffff0000, v158
	v_pk_fma_f32 v[120:121], v[120:121], v[234:235], v[236:237]
	v_lshlrev_b32_e32 v234, 16, v175
	v_and_b32_e32 v235, 0xffff0000, v175
	v_lshlrev_b32_e32 v236, 16, v159
	v_and_b32_e32 v237, 0xffff0000, v159
	v_pk_fma_f32 v[122:123], v[122:123], v[234:235], v[236:237]
; __device__ __forceinline__ float fsigmoid(float v) { return __builtin_amdgcn_rcpf(1.f + __builtin_amdgcn_exp2f(-LOG2E * v)); }
; __device__ __forceinline__ u32x4 pack8(f32x4 a, f32x4 b) { u32x4 w; w.x = cvt_pk(a[0], a[1]); w.y = cvt_pk(a[2], a[3]); w.z = cvt_pk(b[0], b[1]); w.w = cvt_pk(b[2], b[3]); return w; }
;     __device__ __forceinline__ void operator()(EPI_ARGS) const {
;     ...
;                     f32x4 g0 = acc[ai][bj][m][0] * rs, g1 = acc[ai][bj][m][1] * rs;
; #pragma unroll
;                     for (int e = 0; e < 4; ++e) { g0[e] = fsigmoid(g0[e]); g1[e] = fsigmoid(g1[e]); }
;                     f32x4 v0, v1;
;                     v0[0] = bflo(xv.x) + g0[0] * bflo(ev.x); v0[1] = bfhi(xv.x) + g0[1] * bfhi(ev.x); v0[2] = bflo(xv.y) + g0[2] * bflo(ev.y); v0[3] = bfhi(xv.y) + g0[3] * bfhi(ev.y);
;                     v1[0] = bflo(xv.z) + g1[0] * bflo(ev.z); v1[1] = bfhi(xv.z) + g1[1] * bfhi(ev.z); v1[2] = bflo(xv.w) + g1[2] * bflo(ev.w); v1[3] = bfhi(xv.w) + g1[3] * bfhi(ev.w);
;                     *(u32x4*)(E + o) = pack8(v0, v1);
;                     s += ((v0[0] * v0[0] + v0[1] * v0[1]) + (v0[2] * v0[2] + v0[3] * v0[3])) + ((v1[0] * v1[0] + v1[1] * v1[1]) + (v1[2] * v1[2] + v1[3] * v1[3])); }
;                 s += __shfl_xor(s, 16); s += __shfl_xor(s, 32);
;                 if (fq == 0) ss_out[(size_t)row * 16 + u.pn * 4 + wc] = s; __builtin_amdgcn_sched_barrier(0); }
	v_pk_mul_f32 v[238:239], v[124:125], v[124:125]
	v_pk_mul_f32 v[240:241], v[126:127], v[126:127]
	v_pk_mul_f32 v[242:243], v[120:121], v[120:121]
	v_pk_mul_f32 v[244:245], v[122:123], v[122:123]
	v_add_f32_e32 v238, v238, v239
	v_add_f32_e32 v240, v240, v241
	v_add_f32_e32 v242, v242, v243
	v_add_f32_e32 v244, v244, v245
	v_add_f32_e32 v238, v238, v240
	v_add_f32_e32 v242, v242, v244
	v_add_f32_e32 v246, v238, v242
	v_cvt_pk_bf16_f32 v140, v124, v125
	v_cvt_pk_bf16_f32 v141, v126, v127
	v_cvt_pk_bf16_f32 v142, v120, v121
	v_cvt_pk_bf16_f32 v143, v122, v123
	global_store_dwordx4 v223, v[140:143], s[24:25]
	v_mul_f32_e32 v116, v226, v116
	v_mul_f32_e32 v117, v226, v117
	v_mul_f32_e32 v118, v226, v118
	v_mul_f32_e32 v119, v226, v119
	v_mul_f32_e32 v112, v226, v112
	v_mul_f32_e32 v113, v226, v113
	v_mul_f32_e32 v114, v226, v114
	v_mul_f32_e32 v115, v226, v115
	v_mul_f32_e32 v116, 0xbfb8aa3b, v116
	v_mul_f32_e32 v117, 0xbfb8aa3b, v117
	v_mul_f32_e32 v118, 0xbfb8aa3b, v118
	v_mul_f32_e32 v119, 0xbfb8aa3b, v119
	v_mul_f32_e32 v112, 0xbfb8aa3b, v112
	v_mul_f32_e32 v113, 0xbfb8aa3b, v113
	v_mul_f32_e32 v114, 0xbfb8aa3b, v114
	v_mul_f32_e32 v115, 0xbfb8aa3b, v115
	v_exp_f32_e32 v116, v116
	v_exp_f32_e32 v117, v117
	v_exp_f32_e32 v118, v118
	v_exp_f32_e32 v119, v119
	v_exp_f32_e32 v112, v112
	v_exp_f32_e32 v113, v113
	v_exp_f32_e32 v114, v114
	v_exp_f32_e32 v115, v115
	v_add_f32_e32 v116, 1.0, v116
	v_add_f32_e32 v117, 1.0, v117
	v_add_f32_e32 v118, 1.0, v118
	v_add_f32_e32 v119, 1.0, v119
	v_add_f32_e32 v112, 1.0, v112
	v_add_f32_e32 v113, 1.0, v113
	v_add_f32_e32 v114, 1.0, v114
	v_add_f32_e32 v115, 1.0, v115
	v_rcp_f32_e32 v116, v116
	v_rcp_f32_e32 v117, v117
	v_rcp_f32_e32 v118, v118
	v_rcp_f32_e32 v119, v119
	v_rcp_f32_e32 v112, v112
	v_rcp_f32_e32 v113, v113
	v_rcp_f32_e32 v114, v114
	v_rcp_f32_e32 v115, v115
	v_lshlrev_b32_e32 v234, 16, v176
	v_and_b32_e32 v235, 0xffff0000, v176
	v_lshlrev_b32_e32 v236, 16, v160
	v_and_b32_e32 v237, 0xffff0000, v160
	v_pk_fma_f32 v[116:117], v[116:117], v[234:235], v[236:237]
	v_lshlrev_b32_e32 v234, 16, v177
	v_and_b32_e32 v235, 0xffff0000, v177
	v_lshlrev_b32_e32 v236, 16, v161
	v_and_b32_e32 v237, 0xffff0000, v161
	v_pk_fma_f32 v[118:119], v[118:119], v[234:235], v[236:237]
	v_lshlrev_b32_e32 v234, 16, v178
	v_and_b32_e32 v235, 0xffff0000, v178
	v_lshlrev_b32_e32 v236, 16, v162
	v_and_b32_e32 v237, 0xffff0000, v162
	v_pk_fma_f32 v[112:113], v[112:113], v[234:235], v[236:237]
	v_lshlrev_b32_e32 v234, 16, v179
	v_and_b32_e32 v235, 0xffff0000, v179
	v_lshlrev_b32_e32 v236, 16, v163
	v_and_b32_e32 v237, 0xffff0000, v163
	v_pk_fma_f32 v[114:115], v[114:115], v[234:235], v[236:237]
	v_pk_mul_f32 v[238:239], v[116:117], v[116:117]
	v_pk_mul_f32 v[240:241], v[118:119], v[118:119]
	v_pk_mul_f32 v[242:243], v[112:113], v[112:113]
	v_pk_mul_f32 v[244:245], v[114:115], v[114:115]
	v_add_f32_e32 v238, v238, v239
	v_add_f32_e32 v240, v240, v241
	v_add_f32_e32 v242, v242, v243
	v_add_f32_e32 v244, v244, v245
	v_add_f32_e32 v238, v238, v240
	v_add_f32_e32 v242, v242, v244
	v_add_f32_e32 v238, v238, v242
	v_cvt_pk_bf16_f32 v144, v116, v117
	v_cvt_pk_bf16_f32 v145, v118, v119
	v_cvt_pk_bf16_f32 v146, v112, v113
	v_cvt_pk_bf16_f32 v147, v114, v115
	global_store_dwordx4 v223, v[144:147], s[24:25] offset:256
	v_add_f32_e32 v246, v246, v238
	ds_bpermute_b32 v240, v224, v246
	s_waitcnt lgkmcnt(0)
	v_add_f32_e32 v246, v246, v240
	ds_bpermute_b32 v240, v225, v246
	s_waitcnt lgkmcnt(0)
	v_add_f32_e32 v246, v246, v240
	s_and_saveexec_b64 s[22:23], vcc
	global_store_dword v222, v246, s[0:1]
	s_or_b64 exec, exec, s[22:23]
	s_add_u32 s24, s72, 0x8000
	s_addc_u32 s25, s73, 0
	s_add_u32 s0, s8, 0x400
	s_addc_u32 s1, s9, 0
	v_mul_f32_e32 v108, v227, v108
	v_mul_f32_e32 v109, v227, v109
	v_mul_f32_e32 v110, v227, v110
	v_mul_f32_e32 v111, v227, v111
	v_mul_f32_e32 v104, v227, v104
	v_mul_f32_e32 v105, v227, v105
	v_mul_f32_e32 v106, v227, v106
	v_mul_f32_e32 v107, v227, v107
	v_mul_f32_e32 v108, 0xbfb8aa3b, v108
	v_mul_f32_e32 v109, 0xbfb8aa3b, v109
	v_mul_f32_e32 v110, 0xbfb8aa3b, v110
	v_mul_f32_e32 v111, 0xbfb8aa3b, v111
	v_mul_f32_e32 v104, 0xbfb8aa3b, v104
	v_mul_f32_e32 v105, 0xbfb8aa3b, v105
	v_mul_f32_e32 v106, 0xbfb8aa3b, v106
	v_mul_f32_e32 v107, 0xbfb8aa3b, v107
	v_exp_f32_e32 v108, v108
	v_exp_f32_e32 v109, v109
	v_exp_f32_e32 v110, v110
	v_exp_f32_e32 v111, v111
	v_exp_f32_e32 v104, v104
	v_exp_f32_e32 v105, v105
	v_exp_f32_e32 v106, v106
	v_exp_f32_e32 v107, v107
	v_add_f32_e32 v108, 1.0, v108
	v_add_f32_e32 v109, 1.0, v109
	v_add_f32_e32 v110, 1.0, v110
	v_add_f32_e32 v111, 1.0, v111
	v_add_f32_e32 v104, 1.0, v104
	v_add_f32_e32 v105, 1.0, v105
	v_add_f32_e32 v106, 1.0, v106
	v_add_f32_e32 v107, 1.0, v107
	v_rcp_f32_e32 v108, v108
	v_rcp_f32_e32 v109, v109
	v_rcp_f32_e32 v110, v110
	v_rcp_f32_e32 v111, v111
	v_rcp_f32_e32 v104, v104
	v_rcp_f32_e32 v105, v105
	v_rcp_f32_e32 v106, v106
	v_rcp_f32_e32 v107, v107
	v_lshlrev_b32_e32 v234, 16, v180
	v_and_b32_e32 v235, 0xffff0000, v180
	v_lshlrev_b32_e32 v236, 16, v164
	v_and_b32_e32 v237, 0xffff0000, v164
	v_pk_fma_f32 v[108:109], v[108:109], v[234:235], v[236:237]
	v_lshlrev_b32_e32 v234, 16, v181
	v_and_b32_e32 v235, 0xffff0000, v181
	v_lshlrev_b32_e32 v236, 16, v165
	v_and_b32_e32 v237, 0xffff0000, v165
	v_pk_fma_f32 v[110:111], v[110:111], v[234:235], v[236:237]
	v_lshlrev_b32_e32 v234, 16, v182
	v_and_b32_e32 v235, 0xffff0000, v182
	v_lshlrev_b32_e32 v236, 16, v166
	v_and_b32_e32 v237, 0xffff0000, v166
	v_pk_fma_f32 v[104:105], v[104:105], v[234:235], v[236:237]
	v_lshlrev_b32_e32 v234, 16, v183
	v_and_b32_e32 v235, 0xffff0000, v183
	v_lshlrev_b32_e32 v236, 16, v167
; __device__ __forceinline__ float fsigmoid(float v) { return __builtin_amdgcn_rcpf(1.f + __builtin_amdgcn_exp2f(-LOG2E * v)); }
; __device__ __forceinline__ u32x4 pack8(f32x4 a, f32x4 b) { u32x4 w; w.x = cvt_pk(a[0], a[1]); w.y = cvt_pk(a[2], a[3]); w.z = cvt_pk(b[0], b[1]); w.w = cvt_pk(b[2], b[3]); return w; }
;     __device__ __forceinline__ void operator()(EPI_ARGS) const {
;     ...
;                     f32x4 g0 = acc[ai][bj][m][0] * rs, g1 = acc[ai][bj][m][1] * rs;
; #pragma unroll
;                     for (int e = 0; e < 4; ++e) { g0[e] = fsigmoid(g0[e]); g1[e] = fsigmoid(g1[e]); }
;                     f32x4 v0, v1;
;                     v0[0] = bflo(xv.x) + g0[0] * bflo(ev.x); v0[1] = bfhi(xv.x) + g0[1] * bfhi(ev.x); v0[2] = bflo(xv.y) + g0[2] * bflo(ev.y); v0[3] = bfhi(xv.y) + g0[3] * bfhi(ev.y);
;                     v1[0] = bflo(xv.z) + g1[0] * bflo(ev.z); v1[1] = bfhi(xv.z) + g1[1] * bfhi(ev.z); v1[2] = bflo(xv.w) + g1[2] * bflo(ev.w); v1[3] = bfhi(xv.w) + g1[3] * bfhi(ev.w);
;                     *(u32x4*)(E + o) = pack8(v0, v1);
;                     s += ((v0[0] * v0[0] + v0[1] * v0[1]) + (v0[2] * v0[2] + v0[3] * v0[3])) + ((v1[0] * v1[0] + v1[1] * v1[1]) + (v1[2] * v1[2] + v1[3] * v1[3])); }
;                 s += __shfl_xor(s, 16); s += __shfl_xor(s, 32);
;                 if (fq == 0) ss_out[(size_t)row * 16 + u.pn * 4 + wc] = s; __builtin_amdgcn_sched_barrier(0); }
	v_and_b32_e32 v237, 0xffff0000, v167
	v_pk_fma_f32 v[106:107], v[106:107], v[234:235], v[236:237]
	v_pk_mul_f32 v[238:239], v[108:109], v[108:109]
	v_pk_mul_f32 v[240:241], v[110:111], v[110:111]
	v_pk_mul_f32 v[242:243], v[104:105], v[104:105]
	v_pk_mul_f32 v[244:245], v[106:107], v[106:107]
	v_add_f32_e32 v238, v238, v239
	v_add_f32_e32 v240, v240, v241
	v_add_f32_e32 v242, v242, v243
	v_add_f32_e32 v244, v244, v245
	v_add_f32_e32 v238, v238, v240
	v_add_f32_e32 v242, v242, v244
	v_add_f32_e32 v246, v238, v242
	v_cvt_pk_bf16_f32 v140, v108, v109
	v_cvt_pk_bf16_f32 v141, v110, v111
	v_cvt_pk_bf16_f32 v142, v104, v105
	v_cvt_pk_bf16_f32 v143, v106, v107
	global_store_dwordx4 v223, v[140:143], s[24:25]
	v_mul_f32_e32 v100, v227, v100
	v_mul_f32_e32 v101, v227, v101
	v_mul_f32_e32 v102, v227, v102
	v_mul_f32_e32 v103, v227, v103
	v_mul_f32_e32 v96, v227, v96
	v_mul_f32_e32 v97, v227, v97
	v_mul_f32_e32 v98, v227, v98
	v_mul_f32_e32 v99, v227, v99
	v_mul_f32_e32 v100, 0xbfb8aa3b, v100
	v_mul_f32_e32 v101, 0xbfb8aa3b, v101
	v_mul_f32_e32 v102, 0xbfb8aa3b, v102
	v_mul_f32_e32 v103, 0xbfb8aa3b, v103
	v_mul_f32_e32 v96, 0xbfb8aa3b, v96
	v_mul_f32_e32 v97, 0xbfb8aa3b, v97
	v_mul_f32_e32 v98, 0xbfb8aa3b, v98
	v_mul_f32_e32 v99, 0xbfb8aa3b, v99
	v_exp_f32_e32 v100, v100
	v_exp_f32_e32 v101, v101
	v_exp_f32_e32 v102, v102
	v_exp_f32_e32 v103, v103
	v_exp_f32_e32 v96, v96
	v_exp_f32_e32 v97, v97
	v_exp_f32_e32 v98, v98
	v_exp_f32_e32 v99, v99
	v_add_f32_e32 v100, 1.0, v100
	v_add_f32_e32 v101, 1.0, v101
	v_add_f32_e32 v102, 1.0, v102
	v_add_f32_e32 v103, 1.0, v103
	v_add_f32_e32 v96, 1.0, v96
	v_add_f32_e32 v97, 1.0, v97
	v_add_f32_e32 v98, 1.0, v98
	v_add_f32_e32 v99, 1.0, v99
	v_rcp_f32_e32 v100, v100
	v_rcp_f32_e32 v101, v101
	v_rcp_f32_e32 v102, v102
	v_rcp_f32_e32 v103, v103
	v_rcp_f32_e32 v96, v96
	v_rcp_f32_e32 v97, v97
	v_rcp_f32_e32 v98, v98
	v_rcp_f32_e32 v99, v99
	v_lshlrev_b32_e32 v234, 16, v186
	v_and_b32_e32 v235, 0xffff0000, v186
	v_lshlrev_b32_e32 v236, 16, v168
	v_and_b32_e32 v237, 0xffff0000, v168
	v_pk_fma_f32 v[100:101], v[100:101], v[234:235], v[236:237]
	v_lshlrev_b32_e32 v234, 16, v187
	v_and_b32_e32 v235, 0xffff0000, v187
	v_lshlrev_b32_e32 v236, 16, v169
	v_and_b32_e32 v237, 0xffff0000, v169
	v_pk_fma_f32 v[102:103], v[102:103], v[234:235], v[236:237]
	v_lshlrev_b32_e32 v234, 16, v188
	v_and_b32_e32 v235, 0xffff0000, v188
	v_lshlrev_b32_e32 v236, 16, v170
	v_and_b32_e32 v237, 0xffff0000, v170
	v_pk_fma_f32 v[96:97], v[96:97], v[234:235], v[236:237]
	v_lshlrev_b32_e32 v234, 16, v189
	v_and_b32_e32 v235, 0xffff0000, v189
	v_lshlrev_b32_e32 v236, 16, v171
	v_and_b32_e32 v237, 0xffff0000, v171
	v_pk_fma_f32 v[98:99], v[98:99], v[234:235], v[236:237]
	v_pk_mul_f32 v[238:239], v[100:101], v[100:101]
	v_pk_mul_f32 v[240:241], v[102:103], v[102:103]
	v_pk_mul_f32 v[242:243], v[96:97], v[96:97]
	v_pk_mul_f32 v[244:245], v[98:99], v[98:99]
	v_add_f32_e32 v238, v238, v239
	v_add_f32_e32 v240, v240, v241
	v_add_f32_e32 v242, v242, v243
	v_add_f32_e32 v244, v244, v245
	v_add_f32_e32 v238, v238, v240
	v_add_f32_e32 v242, v242, v244
	v_add_f32_e32 v238, v238, v242
	v_cvt_pk_bf16_f32 v144, v100, v101
	v_cvt_pk_bf16_f32 v145, v102, v103
	v_cvt_pk_bf16_f32 v146, v96, v97
	v_cvt_pk_bf16_f32 v147, v98, v99
	global_store_dwordx4 v223, v[144:147], s[24:25] offset:256
	v_add_f32_e32 v246, v246, v238
	ds_bpermute_b32 v240, v224, v246
	s_waitcnt lgkmcnt(0)
	v_add_f32_e32 v246, v246, v240
	ds_bpermute_b32 v240, v225, v246
	s_waitcnt lgkmcnt(0)
	v_add_f32_e32 v246, v246, v240
	s_and_saveexec_b64 s[22:23], vcc
	global_store_dword v222, v246, s[0:1]
	s_or_b64 exec, exec, s[22:23]
	s_add_u32 s100, s88, 0x40000
	s_addc_u32 s101, s89, 0
	s_add_u32 s98, s72, 0x40000
	s_addc_u32 s99, s73, 0
	global_load_dwordx4 v[156:159], v223, s[100:101]
	global_load_dwordx4 v[172:175], v223, s[98:99]
	global_load_dwordx4 v[160:163], v223, s[100:101] offset:256
	global_load_dwordx4 v[176:179], v223, s[98:99] offset:256
	s_add_u32 s100, s88, 0x48000
	s_addc_u32 s101, s89, 0
	s_add_u32 s98, s72, 0x48000
	s_addc_u32 s99, s73, 0
	global_load_dwordx4 v[164:167], v223, s[100:101]
	global_load_dwordx4 v[180:183], v223, s[98:99]
	global_load_dwordx4 v[168:171], v223, s[100:101] offset:256
	global_load_dwordx4 v[186:189], v223, s[98:99] offset:256
	s_waitcnt vmcnt(14)
; __device__ __forceinline__ float fsigmoid(float v) { return __builtin_amdgcn_rcpf(1.f + __builtin_amdgcn_exp2f(-LOG2E * v)); }
; __device__ __forceinline__ u32x4 pack8(f32x4 a, f32x4 b) { u32x4 w; w.x = cvt_pk(a[0], a[1]); w.y = cvt_pk(a[2], a[3]); w.z = cvt_pk(b[0], b[1]); w.w = cvt_pk(b[2], b[3]); return w; }
;     __device__ __forceinline__ void operator()(EPI_ARGS) const {
;     ...
;                     f32x4 g0 = acc[ai][bj][m][0] * rs, g1 = acc[ai][bj][m][1] * rs;
; #pragma unroll
;                     for (int e = 0; e < 4; ++e) { g0[e] = fsigmoid(g0[e]); g1[e] = fsigmoid(g1[e]); }
;                     f32x4 v0, v1;
;                     v0[0] = bflo(xv.x) + g0[0] * bflo(ev.x); v0[1] = bfhi(xv.x) + g0[1] * bfhi(ev.x); v0[2] = bflo(xv.y) + g0[2] * bflo(ev.y); v0[3] = bfhi(xv.y) + g0[3] * bfhi(ev.y);
;                     v1[0] = bflo(xv.z) + g1[0] * bflo(ev.z); v1[1] = bfhi(xv.z) + g1[1] * bfhi(ev.z); v1[2] = bflo(xv.w) + g1[2] * bflo(ev.w); v1[3] = bfhi(xv.w) + g1[3] * bfhi(ev.w);
;                     *(u32x4*)(E + o) = pack8(v0, v1);
;                     s += ((v0[0] * v0[0] + v0[1] * v0[1]) + (v0[2] * v0[2] + v0[3] * v0[3])) + ((v1[0] * v1[0] + v1[1] * v1[1]) + (v1[2] * v1[2] + v1[3] * v1[3])); }
;                 s += __shfl_xor(s, 16); s += __shfl_xor(s, 32);
;                 if (fq == 0) ss_out[(size_t)row * 16 + u.pn * 4 + wc] = s; __builtin_amdgcn_sched_barrier(0); }
	s_add_u32 s24, s72, 0x10000
	s_addc_u32 s25, s73, 0
	s_add_u32 s0, s8, 0x800
	s_addc_u32 s1, s9, 0
	v_mul_f32_e32 v92, v228, v92
	v_mul_f32_e32 v93, v228, v93
	v_mul_f32_e32 v94, v228, v94
	v_mul_f32_e32 v95, v228, v95
	v_mul_f32_e32 v88, v228, v88
	v_mul_f32_e32 v89, v228, v89
	v_mul_f32_e32 v90, v228, v90
	v_mul_f32_e32 v91, v228, v91
	v_mul_f32_e32 v92, 0xbfb8aa3b, v92
	v_mul_f32_e32 v93, 0xbfb8aa3b, v93
	v_mul_f32_e32 v94, 0xbfb8aa3b, v94
	v_mul_f32_e32 v95, 0xbfb8aa3b, v95
	v_mul_f32_e32 v88, 0xbfb8aa3b, v88
	v_mul_f32_e32 v89, 0xbfb8aa3b, v89
	v_mul_f32_e32 v90, 0xbfb8aa3b, v90
	v_mul_f32_e32 v91, 0xbfb8aa3b, v91
	v_exp_f32_e32 v92, v92
	v_exp_f32_e32 v93, v93
	v_exp_f32_e32 v94, v94
	v_exp_f32_e32 v95, v95
	v_exp_f32_e32 v88, v88
	v_exp_f32_e32 v89, v89
	v_exp_f32_e32 v90, v90
	v_exp_f32_e32 v91, v91
	v_add_f32_e32 v92, 1.0, v92
	v_add_f32_e32 v93, 1.0, v93
	v_add_f32_e32 v94, 1.0, v94
	v_add_f32_e32 v95, 1.0, v95
	v_add_f32_e32 v88, 1.0, v88
	v_add_f32_e32 v89, 1.0, v89
	v_add_f32_e32 v90, 1.0, v90
	v_add_f32_e32 v91, 1.0, v91
	v_rcp_f32_e32 v92, v92
	v_rcp_f32_e32 v93, v93
	v_rcp_f32_e32 v94, v94
	v_rcp_f32_e32 v95, v95
	v_rcp_f32_e32 v88, v88
	v_rcp_f32_e32 v89, v89
	v_rcp_f32_e32 v90, v90
	v_rcp_f32_e32 v91, v91
	v_lshlrev_b32_e32 v234, 16, v206
	v_and_b32_e32 v235, 0xffff0000, v206
	v_lshlrev_b32_e32 v236, 16, v190
	v_and_b32_e32 v237, 0xffff0000, v190
	v_pk_fma_f32 v[92:93], v[92:93], v[234:235], v[236:237]
	v_lshlrev_b32_e32 v234, 16, v207
	v_and_b32_e32 v235, 0xffff0000, v207
	v_lshlrev_b32_e32 v236, 16, v191
	v_and_b32_e32 v237, 0xffff0000, v191
	v_pk_fma_f32 v[94:95], v[94:95], v[234:235], v[236:237]
	v_lshlrev_b32_e32 v234, 16, v208
	v_and_b32_e32 v235, 0xffff0000, v208
	v_lshlrev_b32_e32 v236, 16, v192
	v_and_b32_e32 v237, 0xffff0000, v192
	v_pk_fma_f32 v[88:89], v[88:89], v[234:235], v[236:237]
	v_lshlrev_b32_e32 v234, 16, v209
	v_and_b32_e32 v235, 0xffff0000, v209
	v_lshlrev_b32_e32 v236, 16, v193
	v_and_b32_e32 v237, 0xffff0000, v193
	v_pk_fma_f32 v[90:91], v[90:91], v[234:235], v[236:237]
	v_pk_mul_f32 v[238:239], v[92:93], v[92:93]
	v_pk_mul_f32 v[240:241], v[94:95], v[94:95]
	v_pk_mul_f32 v[242:243], v[88:89], v[88:89]
	v_pk_mul_f32 v[244:245], v[90:91], v[90:91]
	v_add_f32_e32 v238, v238, v239
	v_add_f32_e32 v240, v240, v241
	v_add_f32_e32 v242, v242, v243
	v_add_f32_e32 v244, v244, v245
	v_add_f32_e32 v238, v238, v240
	v_add_f32_e32 v242, v242, v244
	v_add_f32_e32 v246, v238, v242
	v_cvt_pk_bf16_f32 v140, v92, v93
	v_cvt_pk_bf16_f32 v141, v94, v95
	v_cvt_pk_bf16_f32 v142, v88, v89
	v_cvt_pk_bf16_f32 v143, v90, v91
	global_store_dwordx4 v223, v[140:143], s[24:25]
	v_mul_f32_e32 v84, v228, v84
	v_mul_f32_e32 v85, v228, v85
	v_mul_f32_e32 v86, v228, v86
	v_mul_f32_e32 v87, v228, v87
	v_mul_f32_e32 v80, v228, v80
	v_mul_f32_e32 v81, v228, v81
	v_mul_f32_e32 v82, v228, v82
	v_mul_f32_e32 v83, v228, v83
	v_mul_f32_e32 v84, 0xbfb8aa3b, v84
	v_mul_f32_e32 v85, 0xbfb8aa3b, v85
	v_mul_f32_e32 v86, 0xbfb8aa3b, v86
	v_mul_f32_e32 v87, 0xbfb8aa3b, v87
	v_mul_f32_e32 v80, 0xbfb8aa3b, v80
	v_mul_f32_e32 v81, 0xbfb8aa3b, v81
	v_mul_f32_e32 v82, 0xbfb8aa3b, v82
	v_mul_f32_e32 v83, 0xbfb8aa3b, v83
	v_exp_f32_e32 v84, v84
	v_exp_f32_e32 v85, v85
	v_exp_f32_e32 v86, v86
	v_exp_f32_e32 v87, v87
	v_exp_f32_e32 v80, v80
	v_exp_f32_e32 v81, v81
	v_exp_f32_e32 v82, v82
	v_exp_f32_e32 v83, v83
	v_add_f32_e32 v84, 1.0, v84
	v_add_f32_e32 v85, 1.0, v85
	v_add_f32_e32 v86, 1.0, v86
	v_add_f32_e32 v87, 1.0, v87
	v_add_f32_e32 v80, 1.0, v80
	v_add_f32_e32 v81, 1.0, v81
	v_add_f32_e32 v82, 1.0, v82
	v_add_f32_e32 v83, 1.0, v83
	v_rcp_f32_e32 v84, v84
	v_rcp_f32_e32 v85, v85
	v_rcp_f32_e32 v86, v86
	v_rcp_f32_e32 v87, v87
	v_rcp_f32_e32 v80, v80
	v_rcp_f32_e32 v81, v81
	v_rcp_f32_e32 v82, v82
	v_rcp_f32_e32 v83, v83
	v_lshlrev_b32_e32 v234, 16, v210
	v_and_b32_e32 v235, 0xffff0000, v210
	v_lshlrev_b32_e32 v236, 16, v194
	v_and_b32_e32 v237, 0xffff0000, v194
	v_pk_fma_f32 v[84:85], v[84:85], v[234:235], v[236:237]
	v_lshlrev_b32_e32 v234, 16, v211
	v_and_b32_e32 v235, 0xffff0000, v211
	v_lshlrev_b32_e32 v236, 16, v195
	v_and_b32_e32 v237, 0xffff0000, v195
	v_pk_fma_f32 v[86:87], v[86:87], v[234:235], v[236:237]
	v_lshlrev_b32_e32 v234, 16, v212
	v_and_b32_e32 v235, 0xffff0000, v212
	v_lshlrev_b32_e32 v236, 16, v196
	v_and_b32_e32 v237, 0xffff0000, v196
	v_pk_fma_f32 v[80:81], v[80:81], v[234:235], v[236:237]
	v_lshlrev_b32_e32 v234, 16, v213
	v_and_b32_e32 v235, 0xffff0000, v213
	v_lshlrev_b32_e32 v236, 16, v197
	v_and_b32_e32 v237, 0xffff0000, v197
	v_pk_fma_f32 v[82:83], v[82:83], v[234:235], v[236:237]
	v_pk_mul_f32 v[238:239], v[84:85], v[84:85]
	v_pk_mul_f32 v[240:241], v[86:87], v[86:87]
	v_pk_mul_f32 v[242:243], v[80:81], v[80:81]
	v_pk_mul_f32 v[244:245], v[82:83], v[82:83]
	v_add_f32_e32 v238, v238, v239
	v_add_f32_e32 v240, v240, v241
	v_add_f32_e32 v242, v242, v243
	v_add_f32_e32 v244, v244, v245
	v_add_f32_e32 v238, v238, v240
	v_add_f32_e32 v242, v242, v244
	v_add_f32_e32 v238, v238, v242
	v_cvt_pk_bf16_f32 v144, v84, v85
	v_cvt_pk_bf16_f32 v145, v86, v87
	v_cvt_pk_bf16_f32 v146, v80, v81
	v_cvt_pk_bf16_f32 v147, v82, v83
	global_store_dwordx4 v223, v[144:147], s[24:25] offset:256
	v_add_f32_e32 v246, v246, v238
	ds_bpermute_b32 v240, v224, v246
	s_waitcnt lgkmcnt(0)
	v_add_f32_e32 v246, v246, v240
	ds_bpermute_b32 v240, v225, v246
	s_waitcnt lgkmcnt(0)
; __device__ __forceinline__ float fsigmoid(float v) { return __builtin_amdgcn_rcpf(1.f + __builtin_amdgcn_exp2f(-LOG2E * v)); }
; __device__ __forceinline__ u32x4 pack8(f32x4 a, f32x4 b) { u32x4 w; w.x = cvt_pk(a[0], a[1]); w.y = cvt_pk(a[2], a[3]); w.z = cvt_pk(b[0], b[1]); w.w = cvt_pk(b[2], b[3]); return w; }
;     __device__ __forceinline__ void operator()(EPI_ARGS) const {
;     ...
;                     f32x4 g0 = acc[ai][bj][m][0] * rs, g1 = acc[ai][bj][m][1] * rs;
; #pragma unroll
;                     for (int e = 0; e < 4; ++e) { g0[e] = fsigmoid(g0[e]); g1[e] = fsigmoid(g1[e]); }
;                     f32x4 v0, v1;
;                     v0[0] = bflo(xv.x) + g0[0] * bflo(ev.x); v0[1] = bfhi(xv.x) + g0[1] * bfhi(ev.x); v0[2] = bflo(xv.y) + g0[2] * bflo(ev.y); v0[3] = bfhi(xv.y) + g0[3] * bfhi(ev.y);
;                     v1[0] = bflo(xv.z) + g1[0] * bflo(ev.z); v1[1] = bfhi(xv.z) + g1[1] * bfhi(ev.z); v1[2] = bflo(xv.w) + g1[2] * bflo(ev.w); v1[3] = bfhi(xv.w) + g1[3] * bfhi(ev.w);
;                     *(u32x4*)(E + o) = pack8(v0, v1);
;                     s += ((v0[0] * v0[0] + v0[1] * v0[1]) + (v0[2] * v0[2] + v0[3] * v0[3])) + ((v1[0] * v1[0] + v1[1] * v1[1]) + (v1[2] * v1[2] + v1[3] * v1[3])); }
;                 s += __shfl_xor(s, 16); s += __shfl_xor(s, 32);
;                 if (fq == 0) ss_out[(size_t)row * 16 + u.pn * 4 + wc] = s; __builtin_amdgcn_sched_barrier(0); }
	v_add_f32_e32 v246, v246, v240
	s_and_saveexec_b64 s[22:23], vcc
	global_store_dword v222, v246, s[0:1]
	s_or_b64 exec, exec, s[22:23]
	s_add_u32 s24, s72, 0x18000
	s_addc_u32 s25, s73, 0
	s_add_u32 s0, s8, 0xc00
	s_addc_u32 s1, s9, 0
	v_mul_f32_e32 v76, v229, v76
	v_mul_f32_e32 v77, v229, v77
	v_mul_f32_e32 v78, v229, v78
	v_mul_f32_e32 v79, v229, v79
	v_mul_f32_e32 v72, v229, v72
	v_mul_f32_e32 v73, v229, v73
	v_mul_f32_e32 v74, v229, v74
	v_mul_f32_e32 v75, v229, v75
	v_mul_f32_e32 v76, 0xbfb8aa3b, v76
	v_mul_f32_e32 v77, 0xbfb8aa3b, v77
	v_mul_f32_e32 v78, 0xbfb8aa3b, v78
	v_mul_f32_e32 v79, 0xbfb8aa3b, v79
	v_mul_f32_e32 v72, 0xbfb8aa3b, v72
	v_mul_f32_e32 v73, 0xbfb8aa3b, v73
	v_mul_f32_e32 v74, 0xbfb8aa3b, v74
	v_mul_f32_e32 v75, 0xbfb8aa3b, v75
	v_exp_f32_e32 v76, v76
	v_exp_f32_e32 v77, v77
	v_exp_f32_e32 v78, v78
	v_exp_f32_e32 v79, v79
	v_exp_f32_e32 v72, v72
	v_exp_f32_e32 v73, v73
	v_exp_f32_e32 v74, v74
	v_exp_f32_e32 v75, v75
	v_add_f32_e32 v76, 1.0, v76
	v_add_f32_e32 v77, 1.0, v77
	v_add_f32_e32 v78, 1.0, v78
	v_add_f32_e32 v79, 1.0, v79
	v_add_f32_e32 v72, 1.0, v72
	v_add_f32_e32 v73, 1.0, v73
	v_add_f32_e32 v74, 1.0, v74
	v_add_f32_e32 v75, 1.0, v75
	v_rcp_f32_e32 v76, v76
	v_rcp_f32_e32 v77, v77
	v_rcp_f32_e32 v78, v78
	v_rcp_f32_e32 v79, v79
	v_rcp_f32_e32 v72, v72
	v_rcp_f32_e32 v73, v73
	v_rcp_f32_e32 v74, v74
	v_rcp_f32_e32 v75, v75
	v_lshlrev_b32_e32 v234, 16, v214
	v_and_b32_e32 v235, 0xffff0000, v214
	v_lshlrev_b32_e32 v236, 16, v198
	v_and_b32_e32 v237, 0xffff0000, v198
	v_pk_fma_f32 v[76:77], v[76:77], v[234:235], v[236:237]
	v_lshlrev_b32_e32 v234, 16, v215
	v_and_b32_e32 v235, 0xffff0000, v215
	v_lshlrev_b32_e32 v236, 16, v199
	v_and_b32_e32 v237, 0xffff0000, v199
	v_pk_fma_f32 v[78:79], v[78:79], v[234:235], v[236:237]
	v_lshlrev_b32_e32 v234, 16, v216
	v_and_b32_e32 v235, 0xffff0000, v216
	v_lshlrev_b32_e32 v236, 16, v200
	v_and_b32_e32 v237, 0xffff0000, v200
	v_pk_fma_f32 v[72:73], v[72:73], v[234:235], v[236:237]
	v_lshlrev_b32_e32 v234, 16, v217
	v_and_b32_e32 v235, 0xffff0000, v217
	v_lshlrev_b32_e32 v236, 16, v201
	v_and_b32_e32 v237, 0xffff0000, v201
	v_pk_fma_f32 v[74:75], v[74:75], v[234:235], v[236:237]
	v_pk_mul_f32 v[238:239], v[76:77], v[76:77]
	v_pk_mul_f32 v[240:241], v[78:79], v[78:79]
	v_pk_mul_f32 v[242:243], v[72:73], v[72:73]
	v_pk_mul_f32 v[244:245], v[74:75], v[74:75]
	v_add_f32_e32 v238, v238, v239
	v_add_f32_e32 v240, v240, v241
	v_add_f32_e32 v242, v242, v243
	v_add_f32_e32 v244, v244, v245
	v_add_f32_e32 v238, v238, v240
	v_add_f32_e32 v242, v242, v244
	v_add_f32_e32 v246, v238, v242
	v_cvt_pk_bf16_f32 v140, v76, v77
	v_cvt_pk_bf16_f32 v141, v78, v79
	v_cvt_pk_bf16_f32 v142, v72, v73
	v_cvt_pk_bf16_f32 v143, v74, v75
	global_store_dwordx4 v223, v[140:143], s[24:25]
	v_mul_f32_e32 v68, v229, v68
	v_mul_f32_e32 v69, v229, v69
	v_mul_f32_e32 v70, v229, v70
	v_mul_f32_e32 v71, v229, v71
	v_mul_f32_e32 v64, v229, v64
	v_mul_f32_e32 v65, v229, v65
	v_mul_f32_e32 v66, v229, v66
	v_mul_f32_e32 v67, v229, v67
	v_mul_f32_e32 v68, 0xbfb8aa3b, v68
	v_mul_f32_e32 v69, 0xbfb8aa3b, v69
	v_mul_f32_e32 v70, 0xbfb8aa3b, v70
	v_mul_f32_e32 v71, 0xbfb8aa3b, v71
	v_mul_f32_e32 v64, 0xbfb8aa3b, v64
	v_mul_f32_e32 v65, 0xbfb8aa3b, v65
	v_mul_f32_e32 v66, 0xbfb8aa3b, v66
	v_mul_f32_e32 v67, 0xbfb8aa3b, v67
	v_exp_f32_e32 v68, v68
	v_exp_f32_e32 v69, v69
	v_exp_f32_e32 v70, v70
	v_exp_f32_e32 v71, v71
	v_exp_f32_e32 v64, v64
	v_exp_f32_e32 v65, v65
	v_exp_f32_e32 v66, v66
	v_exp_f32_e32 v67, v67
	v_add_f32_e32 v68, 1.0, v68
	v_add_f32_e32 v69, 1.0, v69
	v_add_f32_e32 v70, 1.0, v70
	v_add_f32_e32 v71, 1.0, v71
	v_add_f32_e32 v64, 1.0, v64
	v_add_f32_e32 v65, 1.0, v65
	v_add_f32_e32 v66, 1.0, v66
	v_add_f32_e32 v67, 1.0, v67
	v_rcp_f32_e32 v68, v68
	v_rcp_f32_e32 v69, v69
	v_rcp_f32_e32 v70, v70
	v_rcp_f32_e32 v71, v71
	v_rcp_f32_e32 v64, v64
	v_rcp_f32_e32 v65, v65
	v_rcp_f32_e32 v66, v66
	v_rcp_f32_e32 v67, v67
	v_lshlrev_b32_e32 v234, 16, v218
	v_and_b32_e32 v235, 0xffff0000, v218
	v_lshlrev_b32_e32 v236, 16, v202
	v_and_b32_e32 v237, 0xffff0000, v202
	v_pk_fma_f32 v[68:69], v[68:69], v[234:235], v[236:237]
	v_lshlrev_b32_e32 v234, 16, v219
	v_and_b32_e32 v235, 0xffff0000, v219
	v_lshlrev_b32_e32 v236, 16, v203
	v_and_b32_e32 v237, 0xffff0000, v203
	v_pk_fma_f32 v[70:71], v[70:71], v[234:235], v[236:237]
	v_lshlrev_b32_e32 v234, 16, v220
	v_and_b32_e32 v235, 0xffff0000, v220
	v_lshlrev_b32_e32 v236, 16, v204
	v_and_b32_e32 v237, 0xffff0000, v204
	v_pk_fma_f32 v[64:65], v[64:65], v[234:235], v[236:237]
	v_lshlrev_b32_e32 v234, 16, v221
	v_and_b32_e32 v235, 0xffff0000, v221
	v_lshlrev_b32_e32 v236, 16, v205
	v_and_b32_e32 v237, 0xffff0000, v205
	v_pk_fma_f32 v[66:67], v[66:67], v[234:235], v[236:237]
	v_pk_mul_f32 v[238:239], v[68:69], v[68:69]
	v_pk_mul_f32 v[240:241], v[70:71], v[70:71]
	v_pk_mul_f32 v[242:243], v[64:65], v[64:65]
	v_pk_mul_f32 v[244:245], v[66:67], v[66:67]
	v_add_f32_e32 v238, v238, v239
	v_add_f32_e32 v240, v240, v241
	v_add_f32_e32 v242, v242, v243
	v_add_f32_e32 v244, v244, v245
	v_add_f32_e32 v238, v238, v240
	v_add_f32_e32 v242, v242, v244
	v_add_f32_e32 v238, v238, v242
	v_cvt_pk_bf16_f32 v144, v68, v69
	v_cvt_pk_bf16_f32 v145, v70, v71
	v_cvt_pk_bf16_f32 v146, v64, v65
	v_cvt_pk_bf16_f32 v147, v66, v67
	global_store_dwordx4 v223, v[144:147], s[24:25] offset:256
	v_add_f32_e32 v246, v246, v238
	ds_bpermute_b32 v240, v224, v246
	s_waitcnt lgkmcnt(0)
	v_add_f32_e32 v246, v246, v240
	ds_bpermute_b32 v240, v225, v246
	s_waitcnt lgkmcnt(0)
; __device__ __forceinline__ float fsigmoid(float v) { return __builtin_amdgcn_rcpf(1.f + __builtin_amdgcn_exp2f(-LOG2E * v)); }
; __device__ __forceinline__ u32x4 pack8(f32x4 a, f32x4 b) { u32x4 w; w.x = cvt_pk(a[0], a[1]); w.y = cvt_pk(a[2], a[3]); w.z = cvt_pk(b[0], b[1]); w.w = cvt_pk(b[2], b[3]); return w; }
;     __device__ __forceinline__ void operator()(EPI_ARGS) const {
;     ...
;                     f32x4 g0 = acc[ai][bj][m][0] * rs, g1 = acc[ai][bj][m][1] * rs;
; #pragma unroll
;                     for (int e = 0; e < 4; ++e) { g0[e] = fsigmoid(g0[e]); g1[e] = fsigmoid(g1[e]); }
;                     f32x4 v0, v1;
;                     v0[0] = bflo(xv.x) + g0[0] * bflo(ev.x); v0[1] = bfhi(xv.x) + g0[1] * bfhi(ev.x); v0[2] = bflo(xv.y) + g0[2] * bflo(ev.y); v0[3] = bfhi(xv.y) + g0[3] * bfhi(ev.y);
;                     v1[0] = bflo(xv.z) + g1[0] * bflo(ev.z); v1[1] = bfhi(xv.z) + g1[1] * bfhi(ev.z); v1[2] = bflo(xv.w) + g1[2] * bflo(ev.w); v1[3] = bfhi(xv.w) + g1[3] * bfhi(ev.w);
;                     *(u32x4*)(E + o) = pack8(v0, v1);
;                     s += ((v0[0] * v0[0] + v0[1] * v0[1]) + (v0[2] * v0[2] + v0[3] * v0[3])) + ((v1[0] * v1[0] + v1[1] * v1[1]) + (v1[2] * v1[2] + v1[3] * v1[3])); }
;                 s += __shfl_xor(s, 16); s += __shfl_xor(s, 32);
;                 if (fq == 0) ss_out[(size_t)row * 16 + u.pn * 4 + wc] = s; __builtin_amdgcn_sched_barrier(0); }
	v_add_f32_e32 v246, v246, v240
	s_and_saveexec_b64 s[22:23], vcc
	global_store_dword v222, v246, s[0:1]
	s_or_b64 exec, exec, s[22:23]
	s_add_u32 s100, s88, 0x50000
	s_addc_u32 s101, s89, 0
	s_add_u32 s98, s72, 0x50000
	s_addc_u32 s99, s73, 0
	global_load_dwordx4 v[190:193], v223, s[100:101]
	global_load_dwordx4 v[206:209], v223, s[98:99]
	global_load_dwordx4 v[194:197], v223, s[100:101] offset:256
	global_load_dwordx4 v[210:213], v223, s[98:99] offset:256
	s_add_u32 s100, s88, 0x58000
	s_addc_u32 s101, s89, 0
	s_add_u32 s98, s72, 0x58000
	s_addc_u32 s99, s73, 0
	global_load_dwordx4 v[198:201], v223, s[100:101]
	global_load_dwordx4 v[214:217], v223, s[98:99]
	global_load_dwordx4 v[202:205], v223, s[100:101] offset:256
	global_load_dwordx4 v[218:221], v223, s[98:99] offset:256
	s_waitcnt vmcnt(14)
	s_add_u32 s24, s72, 0x40000
	s_addc_u32 s25, s73, 0
	s_add_u32 s0, s8, 0x2000
	s_addc_u32 s1, s9, 0
	v_mul_f32_e32 v60, v230, v60
	v_mul_f32_e32 v61, v230, v61
	v_mul_f32_e32 v62, v230, v62
	v_mul_f32_e32 v63, v230, v63
	v_mul_f32_e32 v56, v230, v56
	v_mul_f32_e32 v57, v230, v57
	v_mul_f32_e32 v58, v230, v58
	v_mul_f32_e32 v59, v230, v59
	v_mul_f32_e32 v60, 0xbfb8aa3b, v60
	v_mul_f32_e32 v61, 0xbfb8aa3b, v61
	v_mul_f32_e32 v62, 0xbfb8aa3b, v62
	v_mul_f32_e32 v63, 0xbfb8aa3b, v63
	v_mul_f32_e32 v56, 0xbfb8aa3b, v56
	v_mul_f32_e32 v57, 0xbfb8aa3b, v57
	v_mul_f32_e32 v58, 0xbfb8aa3b, v58
	v_mul_f32_e32 v59, 0xbfb8aa3b, v59
	v_exp_f32_e32 v60, v60
	v_exp_f32_e32 v61, v61
	v_exp_f32_e32 v62, v62
	v_exp_f32_e32 v63, v63
	v_exp_f32_e32 v56, v56
	v_exp_f32_e32 v57, v57
	v_exp_f32_e32 v58, v58
	v_exp_f32_e32 v59, v59
	v_add_f32_e32 v60, 1.0, v60
	v_add_f32_e32 v61, 1.0, v61
	v_add_f32_e32 v62, 1.0, v62
	v_add_f32_e32 v63, 1.0, v63
	v_add_f32_e32 v56, 1.0, v56
	v_add_f32_e32 v57, 1.0, v57
	v_add_f32_e32 v58, 1.0, v58
	v_add_f32_e32 v59, 1.0, v59
	v_rcp_f32_e32 v60, v60
	v_rcp_f32_e32 v61, v61
	v_rcp_f32_e32 v62, v62
	v_rcp_f32_e32 v63, v63
	v_rcp_f32_e32 v56, v56
	v_rcp_f32_e32 v57, v57
	v_rcp_f32_e32 v58, v58
	v_rcp_f32_e32 v59, v59
	v_lshlrev_b32_e32 v234, 16, v172
	v_and_b32_e32 v235, 0xffff0000, v172
	v_lshlrev_b32_e32 v236, 16, v156
	v_and_b32_e32 v237, 0xffff0000, v156
	v_pk_fma_f32 v[60:61], v[60:61], v[234:235], v[236:237]
	v_lshlrev_b32_e32 v234, 16, v173
	v_and_b32_e32 v235, 0xffff0000, v173
	v_lshlrev_b32_e32 v236, 16, v157
	v_and_b32_e32 v237, 0xffff0000, v157
	v_pk_fma_f32 v[62:63], v[62:63], v[234:235], v[236:237]
	v_lshlrev_b32_e32 v234, 16, v174
	v_and_b32_e32 v235, 0xffff0000, v174
	v_lshlrev_b32_e32 v236, 16, v158
	v_and_b32_e32 v237, 0xffff0000, v158
	v_pk_fma_f32 v[56:57], v[56:57], v[234:235], v[236:237]
	v_lshlrev_b32_e32 v234, 16, v175
	v_and_b32_e32 v235, 0xffff0000, v175
	v_lshlrev_b32_e32 v236, 16, v159
	v_and_b32_e32 v237, 0xffff0000, v159
	v_pk_fma_f32 v[58:59], v[58:59], v[234:235], v[236:237]
	v_pk_mul_f32 v[238:239], v[60:61], v[60:61]
	v_pk_mul_f32 v[240:241], v[62:63], v[62:63]
	v_pk_mul_f32 v[242:243], v[56:57], v[56:57]
	v_pk_mul_f32 v[244:245], v[58:59], v[58:59]
	v_add_f32_e32 v238, v238, v239
	v_add_f32_e32 v240, v240, v241
	v_add_f32_e32 v242, v242, v243
	v_add_f32_e32 v244, v244, v245
	v_add_f32_e32 v238, v238, v240
	v_add_f32_e32 v242, v242, v244
	v_add_f32_e32 v246, v238, v242
	v_cvt_pk_bf16_f32 v140, v60, v61
	v_cvt_pk_bf16_f32 v141, v62, v63
	v_cvt_pk_bf16_f32 v142, v56, v57
	v_cvt_pk_bf16_f32 v143, v58, v59
	global_store_dwordx4 v223, v[140:143], s[24:25]
	v_mul_f32_e32 v52, v230, v52
	v_mul_f32_e32 v53, v230, v53
	v_mul_f32_e32 v54, v230, v54
	v_mul_f32_e32 v55, v230, v55
	v_mul_f32_e32 v48, v230, v48
	v_mul_f32_e32 v49, v230, v49
	v_mul_f32_e32 v50, v230, v50
	v_mul_f32_e32 v51, v230, v51
	v_mul_f32_e32 v52, 0xbfb8aa3b, v52
	v_mul_f32_e32 v53, 0xbfb8aa3b, v53
	v_mul_f32_e32 v54, 0xbfb8aa3b, v54
	v_mul_f32_e32 v55, 0xbfb8aa3b, v55
	v_mul_f32_e32 v48, 0xbfb8aa3b, v48
	v_mul_f32_e32 v49, 0xbfb8aa3b, v49
	v_mul_f32_e32 v50, 0xbfb8aa3b, v50
	v_mul_f32_e32 v51, 0xbfb8aa3b, v51
	v_exp_f32_e32 v52, v52
	v_exp_f32_e32 v53, v53
	v_exp_f32_e32 v54, v54
	v_exp_f32_e32 v55, v55
	v_exp_f32_e32 v48, v48
	v_exp_f32_e32 v49, v49
	v_exp_f32_e32 v50, v50
	v_exp_f32_e32 v51, v51
	v_add_f32_e32 v52, 1.0, v52
	v_add_f32_e32 v53, 1.0, v53
	v_add_f32_e32 v54, 1.0, v54
	v_add_f32_e32 v55, 1.0, v55
	v_add_f32_e32 v48, 1.0, v48
	v_add_f32_e32 v49, 1.0, v49
	v_add_f32_e32 v50, 1.0, v50
	v_add_f32_e32 v51, 1.0, v51
	v_rcp_f32_e32 v52, v52
	v_rcp_f32_e32 v53, v53
	v_rcp_f32_e32 v54, v54
	v_rcp_f32_e32 v55, v55
	v_rcp_f32_e32 v48, v48
	v_rcp_f32_e32 v49, v49
	v_rcp_f32_e32 v50, v50
	v_rcp_f32_e32 v51, v51
	v_lshlrev_b32_e32 v234, 16, v176
	v_and_b32_e32 v235, 0xffff0000, v176
	v_lshlrev_b32_e32 v236, 16, v160
	v_and_b32_e32 v237, 0xffff0000, v160
	v_pk_fma_f32 v[52:53], v[52:53], v[234:235], v[236:237]
	v_lshlrev_b32_e32 v234, 16, v177
	v_and_b32_e32 v235, 0xffff0000, v177
	v_lshlrev_b32_e32 v236, 16, v161
	v_and_b32_e32 v237, 0xffff0000, v161
	v_pk_fma_f32 v[54:55], v[54:55], v[234:235], v[236:237]
	v_lshlrev_b32_e32 v234, 16, v178
	v_and_b32_e32 v235, 0xffff0000, v178
	v_lshlrev_b32_e32 v236, 16, v162
	v_and_b32_e32 v237, 0xffff0000, v162
	v_pk_fma_f32 v[48:49], v[48:49], v[234:235], v[236:237]
	v_lshlrev_b32_e32 v234, 16, v179
	v_and_b32_e32 v235, 0xffff0000, v179
	v_lshlrev_b32_e32 v236, 16, v163
	v_and_b32_e32 v237, 0xffff0000, v163
	v_pk_fma_f32 v[50:51], v[50:51], v[234:235], v[236:237]
	v_pk_mul_f32 v[238:239], v[52:53], v[52:53]
	v_pk_mul_f32 v[240:241], v[54:55], v[54:55]
	v_pk_mul_f32 v[242:243], v[48:49], v[48:49]
	v_pk_mul_f32 v[244:245], v[50:51], v[50:51]
	v_add_f32_e32 v238, v238, v239
	v_add_f32_e32 v240, v240, v241
	v_add_f32_e32 v242, v242, v243
	v_add_f32_e32 v244, v244, v245
	v_add_f32_e32 v238, v238, v240
	v_add_f32_e32 v242, v242, v244
	v_add_f32_e32 v238, v238, v242
	v_cvt_pk_bf16_f32 v144, v52, v53
	v_cvt_pk_bf16_f32 v145, v54, v55
	v_cvt_pk_bf16_f32 v146, v48, v49
	v_cvt_pk_bf16_f32 v147, v50, v51
	global_store_dwordx4 v223, v[144:147], s[24:25] offset:256
	v_add_f32_e32 v246, v246, v238
	ds_bpermute_b32 v240, v224, v246
	s_waitcnt lgkmcnt(0)
; __device__ __forceinline__ float fsigmoid(float v) { return __builtin_amdgcn_rcpf(1.f + __builtin_amdgcn_exp2f(-LOG2E * v)); }
; __device__ __forceinline__ u32x4 pack8(f32x4 a, f32x4 b) { u32x4 w; w.x = cvt_pk(a[0], a[1]); w.y = cvt_pk(a[2], a[3]); w.z = cvt_pk(b[0], b[1]); w.w = cvt_pk(b[2], b[3]); return w; }
;     __device__ __forceinline__ void operator()(EPI_ARGS) const {
;     ...
;                     f32x4 g0 = acc[ai][bj][m][0] * rs, g1 = acc[ai][bj][m][1] * rs;
; #pragma unroll
;                     for (int e = 0; e < 4; ++e) { g0[e] = fsigmoid(g0[e]); g1[e] = fsigmoid(g1[e]); }
;                     f32x4 v0, v1;
;                     v0[0] = bflo(xv.x) + g0[0] * bflo(ev.x); v0[1] = bfhi(xv.x) + g0[1] * bfhi(ev.x); v0[2] = bflo(xv.y) + g0[2] * bflo(ev.y); v0[3] = bfhi(xv.y) + g0[3] * bfhi(ev.y);
;                     v1[0] = bflo(xv.z) + g1[0] * bflo(ev.z); v1[1] = bfhi(xv.z) + g1[1] * bfhi(ev.z); v1[2] = bflo(xv.w) + g1[2] * bflo(ev.w); v1[3] = bfhi(xv.w) + g1[3] * bfhi(ev.w);
;                     *(u32x4*)(E + o) = pack8(v0, v1);
;                     s += ((v0[0] * v0[0] + v0[1] * v0[1]) + (v0[2] * v0[2] + v0[3] * v0[3])) + ((v1[0] * v1[0] + v1[1] * v1[1]) + (v1[2] * v1[2] + v1[3] * v1[3])); }
;                 s += __shfl_xor(s, 16); s += __shfl_xor(s, 32);
;                 if (fq == 0) ss_out[(size_t)row * 16 + u.pn * 4 + wc] = s; __builtin_amdgcn_sched_barrier(0); }
	v_add_f32_e32 v246, v246, v240
	ds_bpermute_b32 v240, v225, v246
	s_waitcnt lgkmcnt(0)
	v_add_f32_e32 v246, v246, v240
	s_and_saveexec_b64 s[22:23], vcc
	global_store_dword v222, v246, s[0:1]
	s_or_b64 exec, exec, s[22:23]
	s_add_u32 s24, s72, 0x48000
	s_addc_u32 s25, s73, 0
	s_add_u32 s0, s8, 0x2400
	s_addc_u32 s1, s9, 0
	v_mul_f32_e32 v44, v231, v44
	v_mul_f32_e32 v45, v231, v45
	v_mul_f32_e32 v46, v231, v46
	v_mul_f32_e32 v47, v231, v47
	v_mul_f32_e32 v40, v231, v40
	v_mul_f32_e32 v41, v231, v41
	v_mul_f32_e32 v42, v231, v42
	v_mul_f32_e32 v43, v231, v43
	v_mul_f32_e32 v44, 0xbfb8aa3b, v44
	v_mul_f32_e32 v45, 0xbfb8aa3b, v45
	v_mul_f32_e32 v46, 0xbfb8aa3b, v46
	v_mul_f32_e32 v47, 0xbfb8aa3b, v47
	v_mul_f32_e32 v40, 0xbfb8aa3b, v40
	v_mul_f32_e32 v41, 0xbfb8aa3b, v41
	v_mul_f32_e32 v42, 0xbfb8aa3b, v42
	v_mul_f32_e32 v43, 0xbfb8aa3b, v43
	v_exp_f32_e32 v44, v44
	v_exp_f32_e32 v45, v45
	v_exp_f32_e32 v46, v46
	v_exp_f32_e32 v47, v47
	v_exp_f32_e32 v40, v40
	v_exp_f32_e32 v41, v41
	v_exp_f32_e32 v42, v42
	v_exp_f32_e32 v43, v43
	v_add_f32_e32 v44, 1.0, v44
	v_add_f32_e32 v45, 1.0, v45
	v_add_f32_e32 v46, 1.0, v46
	v_add_f32_e32 v47, 1.0, v47
	v_add_f32_e32 v40, 1.0, v40
	v_add_f32_e32 v41, 1.0, v41
	v_add_f32_e32 v42, 1.0, v42
	v_add_f32_e32 v43, 1.0, v43
	v_rcp_f32_e32 v44, v44
	v_rcp_f32_e32 v45, v45
	v_rcp_f32_e32 v46, v46
	v_rcp_f32_e32 v47, v47
	v_rcp_f32_e32 v40, v40
	v_rcp_f32_e32 v41, v41
	v_rcp_f32_e32 v42, v42
	v_rcp_f32_e32 v43, v43
	v_lshlrev_b32_e32 v234, 16, v180
	v_and_b32_e32 v235, 0xffff0000, v180
	v_lshlrev_b32_e32 v236, 16, v164
	v_and_b32_e32 v237, 0xffff0000, v164
	v_pk_fma_f32 v[44:45], v[44:45], v[234:235], v[236:237]
	v_lshlrev_b32_e32 v234, 16, v181
	v_and_b32_e32 v235, 0xffff0000, v181
	v_lshlrev_b32_e32 v236, 16, v165
	v_and_b32_e32 v237, 0xffff0000, v165
	v_pk_fma_f32 v[46:47], v[46:47], v[234:235], v[236:237]
	v_lshlrev_b32_e32 v234, 16, v182
	v_and_b32_e32 v235, 0xffff0000, v182
	v_lshlrev_b32_e32 v236, 16, v166
	v_and_b32_e32 v237, 0xffff0000, v166
	v_pk_fma_f32 v[40:41], v[40:41], v[234:235], v[236:237]
	v_lshlrev_b32_e32 v234, 16, v183
	v_and_b32_e32 v235, 0xffff0000, v183
	v_lshlrev_b32_e32 v236, 16, v167
	v_and_b32_e32 v237, 0xffff0000, v167
	v_pk_fma_f32 v[42:43], v[42:43], v[234:235], v[236:237]
	v_pk_mul_f32 v[238:239], v[44:45], v[44:45]
	v_pk_mul_f32 v[240:241], v[46:47], v[46:47]
	v_pk_mul_f32 v[242:243], v[40:41], v[40:41]
	v_pk_mul_f32 v[244:245], v[42:43], v[42:43]
	v_add_f32_e32 v238, v238, v239
	v_add_f32_e32 v240, v240, v241
	v_add_f32_e32 v242, v242, v243
	v_add_f32_e32 v244, v244, v245
	v_add_f32_e32 v238, v238, v240
	v_add_f32_e32 v242, v242, v244
	v_add_f32_e32 v246, v238, v242
	v_cvt_pk_bf16_f32 v140, v44, v45
	v_cvt_pk_bf16_f32 v141, v46, v47
	v_cvt_pk_bf16_f32 v142, v40, v41
	v_cvt_pk_bf16_f32 v143, v42, v43
	global_store_dwordx4 v223, v[140:143], s[24:25]
	v_mul_f32_e32 v36, v231, v36
	v_mul_f32_e32 v37, v231, v37
	v_mul_f32_e32 v38, v231, v38
	v_mul_f32_e32 v39, v231, v39
	v_mul_f32_e32 v32, v231, v32
	v_mul_f32_e32 v33, v231, v33
	v_mul_f32_e32 v34, v231, v34
	v_mul_f32_e32 v35, v231, v35
	v_mul_f32_e32 v36, 0xbfb8aa3b, v36
	v_mul_f32_e32 v37, 0xbfb8aa3b, v37
	v_mul_f32_e32 v38, 0xbfb8aa3b, v38
	v_mul_f32_e32 v39, 0xbfb8aa3b, v39
	v_mul_f32_e32 v32, 0xbfb8aa3b, v32
	v_mul_f32_e32 v33, 0xbfb8aa3b, v33
	v_mul_f32_e32 v34, 0xbfb8aa3b, v34
	v_mul_f32_e32 v35, 0xbfb8aa3b, v35
	v_exp_f32_e32 v36, v36
	v_exp_f32_e32 v37, v37
	v_exp_f32_e32 v38, v38
	v_exp_f32_e32 v39, v39
	v_exp_f32_e32 v32, v32
	v_exp_f32_e32 v33, v33
	v_exp_f32_e32 v34, v34
	v_exp_f32_e32 v35, v35
	v_add_f32_e32 v36, 1.0, v36
	v_add_f32_e32 v37, 1.0, v37
	v_add_f32_e32 v38, 1.0, v38
	v_add_f32_e32 v39, 1.0, v39
	v_add_f32_e32 v32, 1.0, v32
	v_add_f32_e32 v33, 1.0, v33
	v_add_f32_e32 v34, 1.0, v34
	v_add_f32_e32 v35, 1.0, v35
	v_rcp_f32_e32 v36, v36
	v_rcp_f32_e32 v37, v37
	v_rcp_f32_e32 v38, v38
	v_rcp_f32_e32 v39, v39
	v_rcp_f32_e32 v32, v32
	v_rcp_f32_e32 v33, v33
	v_rcp_f32_e32 v34, v34
	v_rcp_f32_e32 v35, v35
	v_lshlrev_b32_e32 v234, 16, v186
	v_and_b32_e32 v235, 0xffff0000, v186
	v_lshlrev_b32_e32 v236, 16, v168
	v_and_b32_e32 v237, 0xffff0000, v168
	v_pk_fma_f32 v[36:37], v[36:37], v[234:235], v[236:237]
	v_lshlrev_b32_e32 v234, 16, v187
	v_and_b32_e32 v235, 0xffff0000, v187
	v_lshlrev_b32_e32 v236, 16, v169
	v_and_b32_e32 v237, 0xffff0000, v169
	v_pk_fma_f32 v[38:39], v[38:39], v[234:235], v[236:237]
	v_lshlrev_b32_e32 v234, 16, v188
	v_and_b32_e32 v235, 0xffff0000, v188
	v_lshlrev_b32_e32 v236, 16, v170
	v_and_b32_e32 v237, 0xffff0000, v170
	v_pk_fma_f32 v[32:33], v[32:33], v[234:235], v[236:237]
	v_lshlrev_b32_e32 v234, 16, v189
	v_and_b32_e32 v235, 0xffff0000, v189
	v_lshlrev_b32_e32 v236, 16, v171
	v_and_b32_e32 v237, 0xffff0000, v171
	v_pk_fma_f32 v[34:35], v[34:35], v[234:235], v[236:237]
	v_pk_mul_f32 v[238:239], v[36:37], v[36:37]
	v_pk_mul_f32 v[240:241], v[38:39], v[38:39]
	v_pk_mul_f32 v[242:243], v[32:33], v[32:33]
	v_pk_mul_f32 v[244:245], v[34:35], v[34:35]
	v_add_f32_e32 v238, v238, v239
	v_add_f32_e32 v240, v240, v241
	v_add_f32_e32 v242, v242, v243
	v_add_f32_e32 v244, v244, v245
	v_add_f32_e32 v238, v238, v240
	v_add_f32_e32 v242, v242, v244
	v_add_f32_e32 v238, v238, v242
	v_cvt_pk_bf16_f32 v144, v36, v37
	v_cvt_pk_bf16_f32 v145, v38, v39
	v_cvt_pk_bf16_f32 v146, v32, v33
	v_cvt_pk_bf16_f32 v147, v34, v35
	global_store_dwordx4 v223, v[144:147], s[24:25] offset:256
	v_add_f32_e32 v246, v246, v238
	ds_bpermute_b32 v240, v224, v246
	s_waitcnt lgkmcnt(0)
	v_add_f32_e32 v246, v246, v240
	ds_bpermute_b32 v240, v225, v246
	s_waitcnt lgkmcnt(0)
; __device__ __forceinline__ float fsigmoid(float v) { return __builtin_amdgcn_rcpf(1.f + __builtin_amdgcn_exp2f(-LOG2E * v)); }
; __device__ __forceinline__ u32x4 pack8(f32x4 a, f32x4 b) { u32x4 w; w.x = cvt_pk(a[0], a[1]); w.y = cvt_pk(a[2], a[3]); w.z = cvt_pk(b[0], b[1]); w.w = cvt_pk(b[2], b[3]); return w; }
;     __device__ __forceinline__ void operator()(EPI_ARGS) const {
;     ...
;                     f32x4 g0 = acc[ai][bj][m][0] * rs, g1 = acc[ai][bj][m][1] * rs;
; #pragma unroll
;                     for (int e = 0; e < 4; ++e) { g0[e] = fsigmoid(g0[e]); g1[e] = fsigmoid(g1[e]); }
;                     f32x4 v0, v1;
;                     v0[0] = bflo(xv.x) + g0[0] * bflo(ev.x); v0[1] = bfhi(xv.x) + g0[1] * bfhi(ev.x); v0[2] = bflo(xv.y) + g0[2] * bflo(ev.y); v0[3] = bfhi(xv.y) + g0[3] * bfhi(ev.y);
;                     v1[0] = bflo(xv.z) + g1[0] * bflo(ev.z); v1[1] = bfhi(xv.z) + g1[1] * bfhi(ev.z); v1[2] = bflo(xv.w) + g1[2] * bflo(ev.w); v1[3] = bfhi(xv.w) + g1[3] * bfhi(ev.w);
;                     *(u32x4*)(E + o) = pack8(v0, v1);
;                     s += ((v0[0] * v0[0] + v0[1] * v0[1]) + (v0[2] * v0[2] + v0[3] * v0[3])) + ((v1[0] * v1[0] + v1[1] * v1[1]) + (v1[2] * v1[2] + v1[3] * v1[3])); }
;                 s += __shfl_xor(s, 16); s += __shfl_xor(s, 32);
;                 if (fq == 0) ss_out[(size_t)row * 16 + u.pn * 4 + wc] = s; __builtin_amdgcn_sched_barrier(0); }
	v_add_f32_e32 v246, v246, v240
	s_and_saveexec_b64 s[22:23], vcc
	global_store_dword v222, v246, s[0:1]
	s_or_b64 exec, exec, s[22:23]
	s_waitcnt vmcnt(6)
	s_add_u32 s24, s72, 0x50000
	s_addc_u32 s25, s73, 0
	s_add_u32 s0, s8, 0x2800
	s_addc_u32 s1, s9, 0
	v_mul_f32_e32 v28, v232, v28
	v_mul_f32_e32 v29, v232, v29
	v_mul_f32_e32 v30, v232, v30
	v_mul_f32_e32 v31, v232, v31
	v_mul_f32_e32 v24, v232, v24
	v_mul_f32_e32 v25, v232, v25
	v_mul_f32_e32 v26, v232, v26
	v_mul_f32_e32 v27, v232, v27
	v_mul_f32_e32 v28, 0xbfb8aa3b, v28
	v_mul_f32_e32 v29, 0xbfb8aa3b, v29
	v_mul_f32_e32 v30, 0xbfb8aa3b, v30
	v_mul_f32_e32 v31, 0xbfb8aa3b, v31
	v_mul_f32_e32 v24, 0xbfb8aa3b, v24
	v_mul_f32_e32 v25, 0xbfb8aa3b, v25
	v_mul_f32_e32 v26, 0xbfb8aa3b, v26
	v_mul_f32_e32 v27, 0xbfb8aa3b, v27
	v_exp_f32_e32 v28, v28
	v_exp_f32_e32 v29, v29
	v_exp_f32_e32 v30, v30
	v_exp_f32_e32 v31, v31
	v_exp_f32_e32 v24, v24
	v_exp_f32_e32 v25, v25
	v_exp_f32_e32 v26, v26
	v_exp_f32_e32 v27, v27
	v_add_f32_e32 v28, 1.0, v28
	v_add_f32_e32 v29, 1.0, v29
	v_add_f32_e32 v30, 1.0, v30
	v_add_f32_e32 v31, 1.0, v31
	v_add_f32_e32 v24, 1.0, v24
	v_add_f32_e32 v25, 1.0, v25
	v_add_f32_e32 v26, 1.0, v26
	v_add_f32_e32 v27, 1.0, v27
	v_rcp_f32_e32 v28, v28
	v_rcp_f32_e32 v29, v29
	v_rcp_f32_e32 v30, v30
	v_rcp_f32_e32 v31, v31
	v_rcp_f32_e32 v24, v24
	v_rcp_f32_e32 v25, v25
	v_rcp_f32_e32 v26, v26
	v_rcp_f32_e32 v27, v27
	v_lshlrev_b32_e32 v234, 16, v206
	v_and_b32_e32 v235, 0xffff0000, v206
	v_lshlrev_b32_e32 v236, 16, v190
	v_and_b32_e32 v237, 0xffff0000, v190
	v_pk_fma_f32 v[28:29], v[28:29], v[234:235], v[236:237]
	v_lshlrev_b32_e32 v234, 16, v207
	v_and_b32_e32 v235, 0xffff0000, v207
	v_lshlrev_b32_e32 v236, 16, v191
	v_and_b32_e32 v237, 0xffff0000, v191
	v_pk_fma_f32 v[30:31], v[30:31], v[234:235], v[236:237]
	v_lshlrev_b32_e32 v234, 16, v208
	v_and_b32_e32 v235, 0xffff0000, v208
	v_lshlrev_b32_e32 v236, 16, v192
	v_and_b32_e32 v237, 0xffff0000, v192
	v_pk_fma_f32 v[24:25], v[24:25], v[234:235], v[236:237]
	v_lshlrev_b32_e32 v234, 16, v209
	v_and_b32_e32 v235, 0xffff0000, v209
	v_lshlrev_b32_e32 v236, 16, v193
	v_and_b32_e32 v237, 0xffff0000, v193
	v_pk_fma_f32 v[26:27], v[26:27], v[234:235], v[236:237]
	v_pk_mul_f32 v[238:239], v[28:29], v[28:29]
	v_pk_mul_f32 v[240:241], v[30:31], v[30:31]
	v_pk_mul_f32 v[242:243], v[24:25], v[24:25]
	v_pk_mul_f32 v[244:245], v[26:27], v[26:27]
	v_add_f32_e32 v238, v238, v239
	v_add_f32_e32 v240, v240, v241
	v_add_f32_e32 v242, v242, v243
	v_add_f32_e32 v244, v244, v245
	v_add_f32_e32 v238, v238, v240
	v_add_f32_e32 v242, v242, v244
	v_add_f32_e32 v246, v238, v242
	v_cvt_pk_bf16_f32 v140, v28, v29
	v_cvt_pk_bf16_f32 v141, v30, v31
	v_cvt_pk_bf16_f32 v142, v24, v25
	v_cvt_pk_bf16_f32 v143, v26, v27
	global_store_dwordx4 v223, v[140:143], s[24:25]
	v_mul_f32_e32 v20, v232, v20
	v_mul_f32_e32 v21, v232, v21
	v_mul_f32_e32 v22, v232, v22
	v_mul_f32_e32 v23, v232, v23
	v_mul_f32_e32 v16, v232, v16
	v_mul_f32_e32 v17, v232, v17
	v_mul_f32_e32 v18, v232, v18
	v_mul_f32_e32 v19, v232, v19
	v_mul_f32_e32 v20, 0xbfb8aa3b, v20
	v_mul_f32_e32 v21, 0xbfb8aa3b, v21
	v_mul_f32_e32 v22, 0xbfb8aa3b, v22
	v_mul_f32_e32 v23, 0xbfb8aa3b, v23
	v_mul_f32_e32 v16, 0xbfb8aa3b, v16
	v_mul_f32_e32 v17, 0xbfb8aa3b, v17
	v_mul_f32_e32 v18, 0xbfb8aa3b, v18
	v_mul_f32_e32 v19, 0xbfb8aa3b, v19
	v_exp_f32_e32 v20, v20
	v_exp_f32_e32 v21, v21
	v_exp_f32_e32 v22, v22
	v_exp_f32_e32 v23, v23
	v_exp_f32_e32 v16, v16
	v_exp_f32_e32 v17, v17
	v_exp_f32_e32 v18, v18
	v_exp_f32_e32 v19, v19
	v_add_f32_e32 v20, 1.0, v20
	v_add_f32_e32 v21, 1.0, v21
	v_add_f32_e32 v22, 1.0, v22
	v_add_f32_e32 v23, 1.0, v23
	v_add_f32_e32 v16, 1.0, v16
	v_add_f32_e32 v17, 1.0, v17
	v_add_f32_e32 v18, 1.0, v18
	v_add_f32_e32 v19, 1.0, v19
	v_rcp_f32_e32 v20, v20
	v_rcp_f32_e32 v21, v21
	v_rcp_f32_e32 v22, v22
	v_rcp_f32_e32 v23, v23
	v_rcp_f32_e32 v16, v16
	v_rcp_f32_e32 v17, v17
	v_rcp_f32_e32 v18, v18
	v_rcp_f32_e32 v19, v19
	v_lshlrev_b32_e32 v234, 16, v210
	v_and_b32_e32 v235, 0xffff0000, v210
	v_lshlrev_b32_e32 v236, 16, v194
	v_and_b32_e32 v237, 0xffff0000, v194
	v_pk_fma_f32 v[20:21], v[20:21], v[234:235], v[236:237]
	v_lshlrev_b32_e32 v234, 16, v211
	v_and_b32_e32 v235, 0xffff0000, v211
	v_lshlrev_b32_e32 v236, 16, v195
	v_and_b32_e32 v237, 0xffff0000, v195
	v_pk_fma_f32 v[22:23], v[22:23], v[234:235], v[236:237]
	v_lshlrev_b32_e32 v234, 16, v212
	v_and_b32_e32 v235, 0xffff0000, v212
	v_lshlrev_b32_e32 v236, 16, v196
	v_and_b32_e32 v237, 0xffff0000, v196
	v_pk_fma_f32 v[16:17], v[16:17], v[234:235], v[236:237]
	v_lshlrev_b32_e32 v234, 16, v213
	v_and_b32_e32 v235, 0xffff0000, v213
	v_lshlrev_b32_e32 v236, 16, v197
	v_and_b32_e32 v237, 0xffff0000, v197
	v_pk_fma_f32 v[18:19], v[18:19], v[234:235], v[236:237]
	v_pk_mul_f32 v[238:239], v[20:21], v[20:21]
	v_pk_mul_f32 v[240:241], v[22:23], v[22:23]
	v_pk_mul_f32 v[242:243], v[16:17], v[16:17]
	v_pk_mul_f32 v[244:245], v[18:19], v[18:19]
	v_add_f32_e32 v238, v238, v239
	v_add_f32_e32 v240, v240, v241
	v_add_f32_e32 v242, v242, v243
	v_add_f32_e32 v244, v244, v245
	v_add_f32_e32 v238, v238, v240
	v_add_f32_e32 v242, v242, v244
	v_add_f32_e32 v238, v238, v242
	v_cvt_pk_bf16_f32 v144, v20, v21
	v_cvt_pk_bf16_f32 v145, v22, v23
	v_cvt_pk_bf16_f32 v146, v16, v17
	v_cvt_pk_bf16_f32 v147, v18, v19
	global_store_dwordx4 v223, v[144:147], s[24:25] offset:256
	v_add_f32_e32 v246, v246, v238
	ds_bpermute_b32 v240, v224, v246
	s_waitcnt lgkmcnt(0)
	v_add_f32_e32 v246, v246, v240
	ds_bpermute_b32 v240, v225, v246
	s_waitcnt lgkmcnt(0)
; __device__ __forceinline__ float fsigmoid(float v) { return __builtin_amdgcn_rcpf(1.f + __builtin_amdgcn_exp2f(-LOG2E * v)); }
; __device__ __forceinline__ u32x4 pack8(f32x4 a, f32x4 b) { u32x4 w; w.x = cvt_pk(a[0], a[1]); w.y = cvt_pk(a[2], a[3]); w.z = cvt_pk(b[0], b[1]); w.w = cvt_pk(b[2], b[3]); return w; }
;     __device__ __forceinline__ void operator()(EPI_ARGS) const {
;     ...
;                     f32x4 g0 = acc[ai][bj][m][0] * rs, g1 = acc[ai][bj][m][1] * rs;
; #pragma unroll
;                     for (int e = 0; e < 4; ++e) { g0[e] = fsigmoid(g0[e]); g1[e] = fsigmoid(g1[e]); }
;                     f32x4 v0, v1;
;                     v0[0] = bflo(xv.x) + g0[0] * bflo(ev.x); v0[1] = bfhi(xv.x) + g0[1] * bfhi(ev.x); v0[2] = bflo(xv.y) + g0[2] * bflo(ev.y); v0[3] = bfhi(xv.y) + g0[3] * bfhi(ev.y);
;                     v1[0] = bflo(xv.z) + g1[0] * bflo(ev.z); v1[1] = bfhi(xv.z) + g1[1] * bfhi(ev.z); v1[2] = bflo(xv.w) + g1[2] * bflo(ev.w); v1[3] = bfhi(xv.w) + g1[3] * bfhi(ev.w);
;                     *(u32x4*)(E + o) = pack8(v0, v1);
;                     s += ((v0[0] * v0[0] + v0[1] * v0[1]) + (v0[2] * v0[2] + v0[3] * v0[3])) + ((v1[0] * v1[0] + v1[1] * v1[1]) + (v1[2] * v1[2] + v1[3] * v1[3])); }
;                 s += __shfl_xor(s, 16); s += __shfl_xor(s, 32);
;                 if (fq == 0) ss_out[(size_t)row * 16 + u.pn * 4 + wc] = s; __builtin_amdgcn_sched_barrier(0); }
	v_add_f32_e32 v246, v246, v240
	s_and_saveexec_b64 s[22:23], vcc
	global_store_dword v222, v246, s[0:1]
	s_or_b64 exec, exec, s[22:23]
	s_add_u32 s24, s72, 0x58000
	s_addc_u32 s25, s73, 0
	s_add_u32 s0, s8, 0x2c00
	s_addc_u32 s1, s9, 0
	v_mul_f32_e32 v12, v233, v12
	v_mul_f32_e32 v13, v233, v13
	v_mul_f32_e32 v14, v233, v14
	v_mul_f32_e32 v15, v233, v15
	v_mul_f32_e32 v8, v233, v8
	v_mul_f32_e32 v9, v233, v9
	v_mul_f32_e32 v10, v233, v10
	v_mul_f32_e32 v11, v233, v11
	v_mul_f32_e32 v12, 0xbfb8aa3b, v12
	v_mul_f32_e32 v13, 0xbfb8aa3b, v13
	v_mul_f32_e32 v14, 0xbfb8aa3b, v14
	v_mul_f32_e32 v15, 0xbfb8aa3b, v15
	v_mul_f32_e32 v8, 0xbfb8aa3b, v8
	v_mul_f32_e32 v9, 0xbfb8aa3b, v9
	v_mul_f32_e32 v10, 0xbfb8aa3b, v10
	v_mul_f32_e32 v11, 0xbfb8aa3b, v11
	v_exp_f32_e32 v12, v12
	v_exp_f32_e32 v13, v13
	v_exp_f32_e32 v14, v14
	v_exp_f32_e32 v15, v15
	v_exp_f32_e32 v8, v8
	v_exp_f32_e32 v9, v9
	v_exp_f32_e32 v10, v10
	v_exp_f32_e32 v11, v11
	v_add_f32_e32 v12, 1.0, v12
	v_add_f32_e32 v13, 1.0, v13
	v_add_f32_e32 v14, 1.0, v14
	v_add_f32_e32 v15, 1.0, v15
	v_add_f32_e32 v8, 1.0, v8
	v_add_f32_e32 v9, 1.0, v9
	v_add_f32_e32 v10, 1.0, v10
	v_add_f32_e32 v11, 1.0, v11
	v_rcp_f32_e32 v12, v12
	v_rcp_f32_e32 v13, v13
	v_rcp_f32_e32 v14, v14
	v_rcp_f32_e32 v15, v15
	v_rcp_f32_e32 v8, v8
	v_rcp_f32_e32 v9, v9
	v_rcp_f32_e32 v10, v10
	v_rcp_f32_e32 v11, v11
	v_lshlrev_b32_e32 v234, 16, v214
	v_and_b32_e32 v235, 0xffff0000, v214
	v_lshlrev_b32_e32 v236, 16, v198
	v_and_b32_e32 v237, 0xffff0000, v198
	v_pk_fma_f32 v[12:13], v[12:13], v[234:235], v[236:237]
	v_lshlrev_b32_e32 v234, 16, v215
	v_and_b32_e32 v235, 0xffff0000, v215
	v_lshlrev_b32_e32 v236, 16, v199
	v_and_b32_e32 v237, 0xffff0000, v199
	v_pk_fma_f32 v[14:15], v[14:15], v[234:235], v[236:237]
	v_lshlrev_b32_e32 v234, 16, v216
	v_and_b32_e32 v235, 0xffff0000, v216
	v_lshlrev_b32_e32 v236, 16, v200
	v_and_b32_e32 v237, 0xffff0000, v200
	v_pk_fma_f32 v[8:9], v[8:9], v[234:235], v[236:237]
	v_lshlrev_b32_e32 v234, 16, v217
	v_and_b32_e32 v235, 0xffff0000, v217
	v_lshlrev_b32_e32 v236, 16, v201
	v_and_b32_e32 v237, 0xffff0000, v201
	v_pk_fma_f32 v[10:11], v[10:11], v[234:235], v[236:237]
	v_pk_mul_f32 v[238:239], v[12:13], v[12:13]
	v_pk_mul_f32 v[240:241], v[14:15], v[14:15]
	v_pk_mul_f32 v[242:243], v[8:9], v[8:9]
	v_pk_mul_f32 v[244:245], v[10:11], v[10:11]
	v_add_f32_e32 v238, v238, v239
	v_add_f32_e32 v240, v240, v241
	v_add_f32_e32 v242, v242, v243
	v_add_f32_e32 v244, v244, v245
	v_add_f32_e32 v238, v238, v240
	v_add_f32_e32 v242, v242, v244
	v_add_f32_e32 v246, v238, v242
	v_cvt_pk_bf16_f32 v140, v12, v13
	v_cvt_pk_bf16_f32 v141, v14, v15
	v_cvt_pk_bf16_f32 v142, v8, v9
	v_cvt_pk_bf16_f32 v143, v10, v11
	global_store_dwordx4 v223, v[140:143], s[24:25]
	v_mul_f32_e32 v4, v233, v4
	v_mul_f32_e32 v5, v233, v5
	v_mul_f32_e32 v6, v233, v6
	v_mul_f32_e32 v7, v233, v7
	v_mul_f32_e32 v0, v233, v0
	v_mul_f32_e32 v1, v233, v1
	v_mul_f32_e32 v2, v233, v2
	v_mul_f32_e32 v3, v233, v3
	v_mul_f32_e32 v4, 0xbfb8aa3b, v4
	v_mul_f32_e32 v5, 0xbfb8aa3b, v5
	v_mul_f32_e32 v6, 0xbfb8aa3b, v6
	v_mul_f32_e32 v7, 0xbfb8aa3b, v7
	v_mul_f32_e32 v0, 0xbfb8aa3b, v0
	v_mul_f32_e32 v1, 0xbfb8aa3b, v1
	v_mul_f32_e32 v2, 0xbfb8aa3b, v2
	v_mul_f32_e32 v3, 0xbfb8aa3b, v3
	v_exp_f32_e32 v4, v4
	v_exp_f32_e32 v5, v5
	v_exp_f32_e32 v6, v6
	v_exp_f32_e32 v7, v7
	v_exp_f32_e32 v0, v0
	v_exp_f32_e32 v1, v1
	v_exp_f32_e32 v2, v2
	v_exp_f32_e32 v3, v3
	v_add_f32_e32 v4, 1.0, v4
	v_add_f32_e32 v5, 1.0, v5
	v_add_f32_e32 v6, 1.0, v6
	v_add_f32_e32 v7, 1.0, v7
	v_add_f32_e32 v0, 1.0, v0
	v_add_f32_e32 v1, 1.0, v1
	v_add_f32_e32 v2, 1.0, v2
	v_add_f32_e32 v3, 1.0, v3
	v_rcp_f32_e32 v4, v4
	v_rcp_f32_e32 v5, v5
	v_rcp_f32_e32 v6, v6
	v_rcp_f32_e32 v7, v7
	v_rcp_f32_e32 v0, v0
	v_rcp_f32_e32 v1, v1
	v_rcp_f32_e32 v2, v2
	v_rcp_f32_e32 v3, v3
	v_lshlrev_b32_e32 v234, 16, v218
	v_and_b32_e32 v235, 0xffff0000, v218
	v_lshlrev_b32_e32 v236, 16, v202
	v_and_b32_e32 v237, 0xffff0000, v202
	v_pk_fma_f32 v[4:5], v[4:5], v[234:235], v[236:237]
	v_lshlrev_b32_e32 v234, 16, v219
	v_and_b32_e32 v235, 0xffff0000, v219
	v_lshlrev_b32_e32 v236, 16, v203
	v_and_b32_e32 v237, 0xffff0000, v203
	v_pk_fma_f32 v[6:7], v[6:7], v[234:235], v[236:237]
	v_lshlrev_b32_e32 v234, 16, v220
	v_and_b32_e32 v235, 0xffff0000, v220
	v_lshlrev_b32_e32 v236, 16, v204
	v_and_b32_e32 v237, 0xffff0000, v204
	v_pk_fma_f32 v[0:1], v[0:1], v[234:235], v[236:237]
	v_lshlrev_b32_e32 v234, 16, v221
	v_and_b32_e32 v235, 0xffff0000, v221
	v_lshlrev_b32_e32 v236, 16, v205
	v_and_b32_e32 v237, 0xffff0000, v205
	v_pk_fma_f32 v[2:3], v[2:3], v[234:235], v[236:237]
	v_pk_mul_f32 v[238:239], v[4:5], v[4:5]
	v_pk_mul_f32 v[240:241], v[6:7], v[6:7]
	v_pk_mul_f32 v[242:243], v[0:1], v[0:1]
	v_pk_mul_f32 v[244:245], v[2:3], v[2:3]
	v_add_f32_e32 v238, v238, v239
	v_add_f32_e32 v240, v240, v241
	v_add_f32_e32 v242, v242, v243
	v_add_f32_e32 v244, v244, v245
	v_add_f32_e32 v238, v238, v240
	v_add_f32_e32 v242, v242, v244
	v_add_f32_e32 v238, v238, v242
	v_cvt_pk_bf16_f32 v144, v4, v5
	v_cvt_pk_bf16_f32 v145, v6, v7
	v_cvt_pk_bf16_f32 v146, v0, v1
	v_cvt_pk_bf16_f32 v147, v2, v3
	global_store_dwordx4 v223, v[144:147], s[24:25] offset:256
	v_add_f32_e32 v246, v246, v238
	ds_bpermute_b32 v240, v224, v246
	s_waitcnt lgkmcnt(0)
	v_add_f32_e32 v246, v246, v240
	ds_bpermute_b32 v240, v225, v246
	s_waitcnt lgkmcnt(0)
	v_add_f32_e32 v246, v246, v240
	s_and_saveexec_b64 s[22:23], vcc
	global_store_dword v222, v246, s[0:1]
	s_or_b64 exec, exec, s[22:23]
	s_andn2_b64 vcc, exec, s[16:17]
	s_mov_b64 s[16:17], -1
	s_cbranch_vccnz .LBB0_1066
	s_andn2_b64 vcc, exec, s[4:5]
	s_cbranch_vccnz .LBB0_1065
	s_barrier
	s_branch .LBB0_1065
